# PL2: code placement: the 10 GEMM K-loop heads placed at 48 mod 64 bytes (the baseline's most common placement); on top of BE1
# speedup vs baseline: 1.0020x; 1.0020x over previous
.LBB0_285:
	s_add_u32 s8, s26, 0x100
	s_addc_u32 s9, s27, 0
	s_add_u32 s18, s20, 0x100
	s_addc_u32 s19, s21, 0
	s_and_b64 s[16:17], s[64:65], exec
	s_cselect_b32 s31, s51, s19
	s_cselect_b32 s30, s50, s18
	s_add_i32 s46, 0, 0x10000
	s_and_b64 s[16:17], s[64:65], exec
	s_cselect_b32 s19, s15, s9
	s_cselect_b32 s18, s14, s8
	s_add_i32 s8, 0, 0x14000
	v_add_u32_e32 v2, s46, v198
	v_add_u32_e32 v132, s8, v198
	ds_read_b128 v[4:7], v2
	ds_read_b128 v[8:11], v2 offset:1024
	ds_read_b128 v[12:15], v2 offset:2048
	ds_read_b128 v[16:19], v2 offset:3072
	ds_read_b128 v[20:23], v132
	ds_read_b128 v[24:27], v132 offset:1024
	ds_read_b128 v[28:31], v132 offset:2048
	ds_read_b128 v[32:35], v132 offset:3072
	s_add_u32 s16, s26, 0x80
	s_addc_u32 s17, s27, 0
	s_add_i32 s42, s85, 0x8000
	s_add_i32 s43, s85, 0xa000
	s_mov_b64 s[28:29], s[16:17]
	s_mov_b32 m0, s42
	s_add_u32 s16, s16, s54
	ds_read_b128 v[36:39], v199 offset:8192
	ds_read_b128 v[40:43], v199 offset:9216
	ds_read_b128 v[44:47], v199 offset:10240
	ds_read_b128 v[48:51], v199 offset:11264
	ds_read_b128 v[52:55], v199 offset:12288
	ds_read_b128 v[56:59], v199 offset:13312
	ds_read_b128 v[60:63], v199 offset:14336
	ds_read_b128 v[64:67], v199 offset:15360
	s_addc_u32 s17, s17, s55
	global_load_lds_dwordx4 v194, s[28:29]
	s_mov_b32 m0, s43
	s_add_i32 s44, s85, 0xc000
	global_load_lds_dwordx4 v195, s[28:29]
	s_mov_b32 m0, s44
	s_add_i32 s45, s85, 0xe000
	s_add_u32 s28, s30, 0x80
	global_load_lds_dwordx4 v194, s[16:17]
	s_mov_b32 m0, s45
	s_addc_u32 s29, s31, 0
	global_load_lds_dwordx4 v195, s[16:17]
	s_waitcnt vmcnt(8)
	s_waitcnt lgkmcnt(0)
	s_barrier
	s_setprio 1
	s_waitcnt lgkmcnt(0)
	v_mfma_f32_16x16x32_bf16 v[68:71], v[4:7], v[36:39], 0
	v_mfma_f32_16x16x32_bf16 v[72:75], v[12:15], v[36:39], 0
	v_mfma_f32_16x16x32_bf16 v[76:79], v[4:7], v[44:47], 0
	v_mfma_f32_16x16x32_bf16 v[80:83], v[12:15], v[44:47], 0
	v_mfma_f32_16x16x32_bf16 v[84:87], v[4:7], v[52:55], 0
	v_mfma_f32_16x16x32_bf16 v[88:91], v[12:15], v[52:55], 0
	v_mfma_f32_16x16x32_bf16 v[92:95], v[4:7], v[60:63], 0
	v_mfma_f32_16x16x32_bf16 v[96:99], v[12:15], v[60:63], 0
	v_mfma_f32_16x16x32_bf16 v[68:71], v[8:11], v[40:43], v[68:71]
	v_mfma_f32_16x16x32_bf16 v[72:75], v[16:19], v[40:43], v[72:75]
	v_mfma_f32_16x16x32_bf16 v[76:79], v[8:11], v[48:51], v[76:79]
	v_mfma_f32_16x16x32_bf16 v[80:83], v[16:19], v[48:51], v[80:83]
	v_mfma_f32_16x16x32_bf16 v[84:87], v[8:11], v[56:59], v[84:87]
	v_mfma_f32_16x16x32_bf16 v[88:91], v[16:19], v[56:59], v[88:91]
	v_mfma_f32_16x16x32_bf16 v[92:95], v[8:11], v[64:67], v[92:95]
	v_mfma_f32_16x16x32_bf16 v[96:99], v[16:19], v[64:67], v[96:99]
	s_setprio 0
	s_setprio 1
	v_mfma_f32_16x16x32_bf16 v[100:103], v[20:23], v[36:39], 0
	v_mfma_f32_16x16x32_bf16 v[36:39], v[28:31], v[36:39], 0
	v_mfma_f32_16x16x32_bf16 v[100:103], v[24:27], v[40:43], v[100:103]
	v_mfma_f32_16x16x32_bf16 v[40:43], v[32:35], v[40:43], v[36:39]
	v_mfma_f32_16x16x32_bf16 v[36:39], v[20:23], v[44:47], 0
	v_mfma_f32_16x16x32_bf16 v[104:107], v[24:27], v[48:51], v[36:39]
	v_mfma_f32_16x16x32_bf16 v[36:39], v[28:31], v[44:47], 0
	v_mfma_f32_16x16x32_bf16 v[48:51], v[32:35], v[48:51], v[36:39]
	v_mfma_f32_16x16x32_bf16 v[36:39], v[20:23], v[52:55], 0
	v_mfma_f32_16x16x32_bf16 v[108:111], v[24:27], v[56:59], v[36:39]
	v_mfma_f32_16x16x32_bf16 v[36:39], v[28:31], v[52:55], 0
	v_mfma_f32_16x16x32_bf16 v[56:59], v[32:35], v[56:59], v[36:39]
	v_mfma_f32_16x16x32_bf16 v[36:39], v[20:23], v[60:63], 0
	v_mfma_f32_16x16x32_bf16 v[112:115], v[24:27], v[64:67], v[36:39]
	v_mfma_f32_16x16x32_bf16 v[36:39], v[28:31], v[60:63], 0
	v_mfma_f32_16x16x32_bf16 v[64:67], v[32:35], v[64:67], v[36:39]
	s_setprio 0
	s_barrier
	s_add_i32 s46, s46, s83
	s_mov_b64 s[16:17], s[30:31]
	s_mov_b32 m0, s46
	s_add_i32 s47, s46, 0x2000
	s_nop 0
	ds_read_b128 v[36:39], v199 offset:24576
	ds_read_b128 v[44:47], v199 offset:25600
	ds_read_b128 v[52:55], v199 offset:26624
	ds_read_b128 v[60:63], v199 offset:27648
	ds_read_b128 v[116:119], v199 offset:28672
	ds_read_b128 v[120:123], v199 offset:29696
	ds_read_b128 v[124:127], v199 offset:30720
	ds_read_b128 v[128:131], v199 offset:31744
	s_nop 0
	global_load_lds_dwordx4 v201, s[16:17]
	s_mov_b32 m0, s47
	s_nop 0
	global_load_lds_dwordx4 v200, s[16:17]
	s_add_u32 s16, s30, s54
	s_addc_u32 s17, s31, s55
	s_add_i32 s30, s8, s83
	s_mov_b32 m0, s30
	s_add_i32 s31, s30, 0x2000
	s_nop 0
	global_load_lds_dwordx4 v201, s[16:17]
	s_mov_b32 m0, s31
	s_nop 0
	global_load_lds_dwordx4 v200, s[16:17]
	s_waitcnt vmcnt(6)
	s_waitcnt lgkmcnt(0)
	s_barrier
	s_setprio 1
	s_waitcnt lgkmcnt(0)
	v_mfma_f32_16x16x32_bf16 v[134:137], v[4:7], v[36:39], 0
	v_mfma_f32_16x16x32_bf16 v[144:147], v[4:7], v[52:55], 0
	v_mfma_f32_16x16x32_bf16 v[152:155], v[4:7], v[116:119], 0
	v_mfma_f32_16x16x32_bf16 v[4:7], v[4:7], v[124:127], 0
	v_mfma_f32_16x16x32_bf16 v[140:143], v[12:15], v[36:39], 0
	v_mfma_f32_16x16x32_bf16 v[148:151], v[12:15], v[52:55], 0
	v_mfma_f32_16x16x32_bf16 v[156:159], v[12:15], v[116:119], 0
	v_mfma_f32_16x16x32_bf16 v[160:163], v[8:11], v[128:131], v[4:7]
	v_mfma_f32_16x16x32_bf16 v[4:7], v[12:15], v[124:127], 0
	v_mfma_f32_16x16x32_bf16 v[136:139], v[8:11], v[44:47], v[134:137]
	v_mfma_f32_16x16x32_bf16 v[140:143], v[16:19], v[44:47], v[140:143]
	v_mfma_f32_16x16x32_bf16 v[144:147], v[8:11], v[60:63], v[144:147]
	v_mfma_f32_16x16x32_bf16 v[148:151], v[16:19], v[60:63], v[148:151]
	v_mfma_f32_16x16x32_bf16 v[152:155], v[8:11], v[120:123], v[152:155]
	v_mfma_f32_16x16x32_bf16 v[156:159], v[16:19], v[120:123], v[156:159]
	v_mfma_f32_16x16x32_bf16 v[164:167], v[16:19], v[128:131], v[4:7]
	s_setprio 0
	s_setprio 1
	v_mfma_f32_16x16x32_bf16 v[4:7], v[20:23], v[36:39], 0
	v_mfma_f32_16x16x32_bf16 v[168:171], v[24:27], v[44:47], v[4:7]
	v_mfma_f32_16x16x32_bf16 v[4:7], v[28:31], v[36:39], 0
	v_mfma_f32_16x16x32_bf16 v[172:175], v[32:35], v[44:47], v[4:7]
	v_mfma_f32_16x16x32_bf16 v[4:7], v[20:23], v[52:55], 0
	v_mfma_f32_16x16x32_bf16 v[176:179], v[24:27], v[60:63], v[4:7]
	v_mfma_f32_16x16x32_bf16 v[4:7], v[28:31], v[52:55], 0
	v_mfma_f32_16x16x32_bf16 v[180:183], v[32:35], v[60:63], v[4:7]
	v_mfma_f32_16x16x32_bf16 v[4:7], v[20:23], v[116:119], 0
	v_mfma_f32_16x16x32_bf16 v[184:187], v[24:27], v[120:123], v[4:7]
	v_mfma_f32_16x16x32_bf16 v[4:7], v[28:31], v[116:119], 0
	v_mfma_f32_16x16x32_bf16 v[120:123], v[32:35], v[120:123], v[4:7]
	v_mfma_f32_16x16x32_bf16 v[4:7], v[20:23], v[124:127], 0
	v_mfma_f32_16x16x32_bf16 v[188:191], v[24:27], v[128:131], v[4:7]
	v_mfma_f32_16x16x32_bf16 v[4:7], v[28:31], v[124:127], 0
	v_mfma_f32_16x16x32_bf16 v[128:131], v[32:35], v[128:131], v[4:7]
	s_setprio 0
	s_barrier
	s_add_i32 s48, 0, 0x18000
	s_add_i32 s8, 0, 0x1c000
	v_add_u32_e32 v133, s48, v198
	v_add_u32_e32 v134, s8, v198
	ds_read_b128 v[116:119], v133
	ds_read_b128 v[124:127], v133 offset:1024
	ds_read_b128 v[202:205], v133 offset:2048
	ds_read_b128 v[206:209], v133 offset:3072
	ds_read_b128 v[216:219], v134
	ds_read_b128 v[220:223], v134 offset:1024
	ds_read_b128 v[224:227], v134 offset:2048
	ds_read_b128 v[228:231], v134 offset:3072
	s_mov_b32 m0, s85
	s_mov_b64 s[16:17], s[18:19]
	ds_read_b128 v[44:47], v199 offset:40960
	ds_read_b128 v[52:55], v199 offset:41984
	ds_read_b128 v[60:63], v199 offset:43008
	ds_read_b128 v[232:235], v199 offset:44032
	ds_read_b128 v[236:239], v199 offset:45056
	ds_read_b128 v[242:245], v199 offset:46080
	ds_read_b128 v[246:249], v199 offset:47104
	ds_read_b128 v[250:253], v199 offset:48128
	s_nop 0
	global_load_lds_dwordx4 v194, s[16:17]
	s_mov_b32 m0, s86
	s_nop 0
	global_load_lds_dwordx4 v195, s[16:17]
	s_add_u32 s16, s18, s54
	s_addc_u32 s17, s19, s55
	s_mov_b32 m0, s87
	s_nop 0
	global_load_lds_dwordx4 v194, s[16:17]
	s_mov_b32 m0, s88
	s_nop 0
	global_load_lds_dwordx4 v195, s[16:17]
	s_waitcnt vmcnt(8)
	s_waitcnt lgkmcnt(0)
	s_barrier
	s_setprio 1
	s_waitcnt lgkmcnt(0)
	v_mfma_f32_16x16x32_bf16 v[4:7], v[116:119], v[44:47], v[68:71]
	v_mfma_f32_16x16x32_bf16 v[4:7], v[124:127], v[52:55], v[4:7]
	v_mfma_f32_16x16x32_bf16 v[8:11], v[202:205], v[44:47], v[72:75]
	v_mfma_f32_16x16x32_bf16 v[8:11], v[206:209], v[52:55], v[8:11]
	v_mfma_f32_16x16x32_bf16 v[12:15], v[116:119], v[60:63], v[76:79]
	v_mfma_f32_16x16x32_bf16 v[12:15], v[124:127], v[232:235], v[12:15]
	v_mfma_f32_16x16x32_bf16 v[16:19], v[202:205], v[60:63], v[80:83]
	v_mfma_f32_16x16x32_bf16 v[16:19], v[206:209], v[232:235], v[16:19]
	v_mfma_f32_16x16x32_bf16 v[20:23], v[116:119], v[236:239], v[84:87]
	v_mfma_f32_16x16x32_bf16 v[20:23], v[124:127], v[242:245], v[20:23]
	v_mfma_f32_16x16x32_bf16 v[24:27], v[202:205], v[236:239], v[88:91]
	v_mfma_f32_16x16x32_bf16 v[24:27], v[206:209], v[242:245], v[24:27]
	v_mfma_f32_16x16x32_bf16 v[28:31], v[116:119], v[246:249], v[92:95]
	v_mfma_f32_16x16x32_bf16 v[28:31], v[124:127], v[250:253], v[28:31]
	v_mfma_f32_16x16x32_bf16 v[32:35], v[202:205], v[246:249], v[96:99]
	v_mfma_f32_16x16x32_bf16 v[32:35], v[206:209], v[250:253], v[32:35]
	s_setprio 0
	s_setprio 1
	v_mfma_f32_16x16x32_bf16 v[36:39], v[216:219], v[44:47], v[100:103]
	v_mfma_f32_16x16x32_bf16 v[40:43], v[224:227], v[44:47], v[40:43]
	v_mfma_f32_16x16x32_bf16 v[36:39], v[220:223], v[52:55], v[36:39]
	v_mfma_f32_16x16x32_bf16 v[40:43], v[228:231], v[52:55], v[40:43]
	v_mfma_f32_16x16x32_bf16 v[44:47], v[216:219], v[60:63], v[104:107]
	v_mfma_f32_16x16x32_bf16 v[48:51], v[224:227], v[60:63], v[48:51]
	v_mfma_f32_16x16x32_bf16 v[52:55], v[216:219], v[236:239], v[108:111]
	v_mfma_f32_16x16x32_bf16 v[56:59], v[224:227], v[236:239], v[56:59]
	v_mfma_f32_16x16x32_bf16 v[60:63], v[216:219], v[246:249], v[112:115]
	v_mfma_f32_16x16x32_bf16 v[64:67], v[224:227], v[246:249], v[64:67]
	v_mfma_f32_16x16x32_bf16 v[44:47], v[220:223], v[232:235], v[44:47]
	v_mfma_f32_16x16x32_bf16 v[48:51], v[228:231], v[232:235], v[48:51]
	v_mfma_f32_16x16x32_bf16 v[52:55], v[220:223], v[242:245], v[52:55]
	v_mfma_f32_16x16x32_bf16 v[56:59], v[228:231], v[242:245], v[56:59]
	v_mfma_f32_16x16x32_bf16 v[60:63], v[220:223], v[250:253], v[60:63]
	v_mfma_f32_16x16x32_bf16 v[64:67], v[228:231], v[250:253], v[64:67]
	s_setprio 0
	s_barrier
	s_add_i32 s48, s48, s83
	s_mov_b64 s[16:17], s[28:29]
	s_mov_b32 m0, s48
	s_add_i32 s49, s48, 0x2000
	ds_read_b128 v[104:107], v199 offset:57344
	ds_read_b128 v[108:111], v199 offset:58368
	ds_read_b128 v[112:115], v199 offset:59392
	ds_read_b128 v[232:235], v199 offset:60416
	ds_read_b128 v[236:239], v199 offset:61440
	ds_read_b128 v[242:245], v199 offset:62464
	ds_read_b128 v[246:249], v199 offset:63488
	ds_read_b128 v[250:253], v199 offset:64512
	s_nop 0
	global_load_lds_dwordx4 v201, s[16:17]
	s_mov_b32 m0, s49
	s_nop 0
	global_load_lds_dwordx4 v200, s[16:17]
	s_add_u32 s16, s28, s54
	s_addc_u32 s17, s29, s55
	s_add_i32 s28, s8, s83
	s_mov_b32 m0, s28
	s_add_i32 s29, s28, 0x2000
	s_nop 0
	global_load_lds_dwordx4 v201, s[16:17]
	s_mov_b32 m0, s29
	s_nop 0
	global_load_lds_dwordx4 v200, s[16:17]
	s_waitcnt vmcnt(6)
	s_waitcnt lgkmcnt(0)
	s_barrier
	s_setprio 1
	s_waitcnt lgkmcnt(0)
	v_mfma_f32_16x16x32_bf16 v[68:71], v[116:119], v[104:107], v[136:139]
	v_mfma_f32_16x16x32_bf16 v[68:71], v[124:127], v[108:111], v[68:71]
	v_mfma_f32_16x16x32_bf16 v[72:75], v[202:205], v[104:107], v[140:143]
	v_mfma_f32_16x16x32_bf16 v[72:75], v[206:209], v[108:111], v[72:75]
	v_mfma_f32_16x16x32_bf16 v[76:79], v[116:119], v[112:115], v[144:147]
	v_mfma_f32_16x16x32_bf16 v[76:79], v[124:127], v[232:235], v[76:79]
	v_mfma_f32_16x16x32_bf16 v[80:83], v[202:205], v[112:115], v[148:151]
	v_mfma_f32_16x16x32_bf16 v[80:83], v[206:209], v[232:235], v[80:83]
	v_mfma_f32_16x16x32_bf16 v[84:87], v[116:119], v[236:239], v[152:155]
	v_mfma_f32_16x16x32_bf16 v[84:87], v[124:127], v[242:245], v[84:87]
	v_mfma_f32_16x16x32_bf16 v[88:91], v[202:205], v[236:239], v[156:159]
	v_mfma_f32_16x16x32_bf16 v[88:91], v[206:209], v[242:245], v[88:91]
	v_mfma_f32_16x16x32_bf16 v[92:95], v[116:119], v[246:249], v[160:163]
	v_mfma_f32_16x16x32_bf16 v[92:95], v[124:127], v[250:253], v[92:95]
	v_mfma_f32_16x16x32_bf16 v[96:99], v[202:205], v[246:249], v[164:167]
	v_mfma_f32_16x16x32_bf16 v[96:99], v[206:209], v[250:253], v[96:99]
	s_setprio 0
	s_setprio 1
	v_mfma_f32_16x16x32_bf16 v[100:103], v[216:219], v[104:107], v[168:171]
	v_mfma_f32_16x16x32_bf16 v[104:107], v[224:227], v[104:107], v[172:175]
	v_mfma_f32_16x16x32_bf16 v[100:103], v[220:223], v[108:111], v[100:103]
	v_mfma_f32_16x16x32_bf16 v[104:107], v[228:231], v[108:111], v[104:107]
	v_mfma_f32_16x16x32_bf16 v[108:111], v[216:219], v[112:115], v[176:179]
	v_mfma_f32_16x16x32_bf16 v[112:115], v[224:227], v[112:115], v[180:183]
	v_mfma_f32_16x16x32_bf16 v[116:119], v[216:219], v[236:239], v[184:187]
	v_mfma_f32_16x16x32_bf16 v[120:123], v[224:227], v[236:239], v[120:123]
	v_mfma_f32_16x16x32_bf16 v[124:127], v[216:219], v[246:249], v[188:191]
	v_mfma_f32_16x16x32_bf16 v[128:131], v[224:227], v[246:249], v[128:131]
	v_mfma_f32_16x16x32_bf16 v[108:111], v[220:223], v[232:235], v[108:111]
	v_mfma_f32_16x16x32_bf16 v[112:115], v[228:231], v[232:235], v[112:115]
	v_mfma_f32_16x16x32_bf16 v[116:119], v[220:223], v[242:245], v[116:119]
	v_mfma_f32_16x16x32_bf16 v[120:123], v[228:231], v[242:245], v[120:123]
	v_mfma_f32_16x16x32_bf16 v[124:127], v[220:223], v[250:253], v[124:127]
	v_mfma_f32_16x16x32_bf16 v[128:131], v[228:231], v[250:253], v[128:131]
	s_setprio 0
	s_barrier
	s_andn2_b64 vcc, exec, s[66:67]
	s_cbranch_vccnz .LBB0_288
	s_add_u32 s52, s20, 0x200
	s_addc_u32 s53, s21, 0
	s_add_u32 s26, s26, 0x200
	s_addc_u32 s27, s27, 0
	s_mov_b32 s72, 4
	.p2align	6
	s_nop 0
	s_nop 0
	s_nop 0
	s_nop 0
	s_nop 0
	s_nop 0
	s_nop 0
	s_nop 0
	s_nop 0
	s_nop 0
	s_nop 0
	s_nop 0

.LBB0_427:
	s_add_u32 s8, s26, 0x100
	s_addc_u32 s9, s27, 0
	s_add_u32 s18, s20, 0x100
	s_addc_u32 s19, s21, 0
	s_and_b64 s[16:17], s[62:63], exec
	s_cselect_b32 s31, s51, s19
	s_cselect_b32 s30, s50, s18
	s_add_i32 s44, 0, 0x10000
	s_and_b64 s[16:17], s[62:63], exec
	s_cselect_b32 s19, s15, s9
	s_cselect_b32 s18, s14, s8
	s_add_i32 s8, 0, 0x14000
	v_add_u32_e32 v2, s44, v198
	v_add_u32_e32 v132, s8, v198
	ds_read_b128 v[4:7], v2
	ds_read_b128 v[8:11], v2 offset:1024
	ds_read_b128 v[12:15], v2 offset:2048
	ds_read_b128 v[16:19], v2 offset:3072
	ds_read_b128 v[20:23], v132
	ds_read_b128 v[24:27], v132 offset:1024
	ds_read_b128 v[28:31], v132 offset:2048
	ds_read_b128 v[32:35], v132 offset:3072
	s_add_u32 s16, s26, 0x80
	s_addc_u32 s17, s27, 0
	s_add_i32 s40, s84, 0x8000
	s_add_i32 s41, s84, 0xa000
	s_mov_b64 s[28:29], s[16:17]
	s_mov_b32 m0, s40
	s_add_u32 s16, s16, s52
	ds_read_b128 v[36:39], v199
	ds_read_b128 v[40:43], v199 offset:1024
	ds_read_b128 v[44:47], v199 offset:2048
	ds_read_b128 v[48:51], v199 offset:3072
	ds_read_b128 v[52:55], v199 offset:4096
	ds_read_b128 v[56:59], v199 offset:5120
	ds_read_b128 v[60:63], v199 offset:6144
	ds_read_b128 v[64:67], v199 offset:7168
	s_addc_u32 s17, s17, s53
	global_load_lds_dwordx4 v194, s[28:29]
	s_mov_b32 m0, s41
	s_add_i32 s42, s84, 0xc000
	global_load_lds_dwordx4 v195, s[28:29]
	s_mov_b32 m0, s42
	s_add_i32 s43, s84, 0xe000
	s_add_u32 s28, s30, 0x80
	global_load_lds_dwordx4 v194, s[16:17]
	s_mov_b32 m0, s43
	s_addc_u32 s29, s31, 0
	global_load_lds_dwordx4 v195, s[16:17]
	s_waitcnt vmcnt(8)
	s_waitcnt lgkmcnt(0)
	s_barrier
	s_setprio 1
	s_waitcnt lgkmcnt(0)
	v_mfma_f32_16x16x32_bf16 v[68:71], v[4:7], v[36:39], 0
	v_mfma_f32_16x16x32_bf16 v[72:75], v[12:15], v[36:39], 0
	v_mfma_f32_16x16x32_bf16 v[76:79], v[4:7], v[44:47], 0
	v_mfma_f32_16x16x32_bf16 v[80:83], v[12:15], v[44:47], 0
	v_mfma_f32_16x16x32_bf16 v[84:87], v[4:7], v[52:55], 0
	v_mfma_f32_16x16x32_bf16 v[88:91], v[12:15], v[52:55], 0
	v_mfma_f32_16x16x32_bf16 v[92:95], v[4:7], v[60:63], 0
	v_mfma_f32_16x16x32_bf16 v[96:99], v[12:15], v[60:63], 0
	v_mfma_f32_16x16x32_bf16 v[68:71], v[8:11], v[40:43], v[68:71]
	v_mfma_f32_16x16x32_bf16 v[72:75], v[16:19], v[40:43], v[72:75]
	v_mfma_f32_16x16x32_bf16 v[76:79], v[8:11], v[48:51], v[76:79]
	v_mfma_f32_16x16x32_bf16 v[80:83], v[16:19], v[48:51], v[80:83]
	v_mfma_f32_16x16x32_bf16 v[84:87], v[8:11], v[56:59], v[84:87]
	v_mfma_f32_16x16x32_bf16 v[88:91], v[16:19], v[56:59], v[88:91]
	v_mfma_f32_16x16x32_bf16 v[92:95], v[8:11], v[64:67], v[92:95]
	v_mfma_f32_16x16x32_bf16 v[96:99], v[16:19], v[64:67], v[96:99]
	s_setprio 0
	s_setprio 1
	v_mfma_f32_16x16x32_bf16 v[100:103], v[20:23], v[36:39], 0
	v_mfma_f32_16x16x32_bf16 v[36:39], v[28:31], v[36:39], 0
	v_mfma_f32_16x16x32_bf16 v[100:103], v[24:27], v[40:43], v[100:103]
	v_mfma_f32_16x16x32_bf16 v[40:43], v[32:35], v[40:43], v[36:39]
	v_mfma_f32_16x16x32_bf16 v[36:39], v[20:23], v[44:47], 0
	v_mfma_f32_16x16x32_bf16 v[104:107], v[24:27], v[48:51], v[36:39]
	v_mfma_f32_16x16x32_bf16 v[36:39], v[28:31], v[44:47], 0
	v_mfma_f32_16x16x32_bf16 v[48:51], v[32:35], v[48:51], v[36:39]
	v_mfma_f32_16x16x32_bf16 v[36:39], v[20:23], v[52:55], 0
	v_mfma_f32_16x16x32_bf16 v[108:111], v[24:27], v[56:59], v[36:39]
	v_mfma_f32_16x16x32_bf16 v[36:39], v[28:31], v[52:55], 0
	v_mfma_f32_16x16x32_bf16 v[56:59], v[32:35], v[56:59], v[36:39]
	v_mfma_f32_16x16x32_bf16 v[36:39], v[20:23], v[60:63], 0
	v_mfma_f32_16x16x32_bf16 v[112:115], v[24:27], v[64:67], v[36:39]
	v_mfma_f32_16x16x32_bf16 v[36:39], v[28:31], v[60:63], 0
	v_mfma_f32_16x16x32_bf16 v[64:67], v[32:35], v[64:67], v[36:39]
	s_setprio 0
	s_barrier
	s_add_i32 s44, s44, s82
	s_mov_b64 s[16:17], s[30:31]
	s_mov_b32 m0, s44
	s_add_i32 s45, s44, 0x2000
	s_nop 0
	ds_read_b128 v[36:39], v199 offset:16384
	ds_read_b128 v[44:47], v199 offset:17408
	ds_read_b128 v[52:55], v199 offset:18432
	ds_read_b128 v[60:63], v199 offset:19456
	ds_read_b128 v[116:119], v199 offset:20480
	ds_read_b128 v[120:123], v199 offset:21504
	ds_read_b128 v[124:127], v199 offset:22528
	ds_read_b128 v[128:131], v199 offset:23552
	s_nop 0
	global_load_lds_dwordx4 v201, s[16:17]
	s_mov_b32 m0, s45
	s_nop 0
	global_load_lds_dwordx4 v200, s[16:17]
	s_add_u32 s16, s30, s52
	s_addc_u32 s17, s31, s53
	s_add_i32 s30, s8, s82
	s_mov_b32 m0, s30
	s_add_i32 s31, s30, 0x2000
	s_nop 0
	global_load_lds_dwordx4 v201, s[16:17]
	s_mov_b32 m0, s31
	s_nop 0
	global_load_lds_dwordx4 v200, s[16:17]
	s_waitcnt vmcnt(6)
	s_waitcnt lgkmcnt(0)
	s_barrier
	s_setprio 1
	s_waitcnt lgkmcnt(0)
	v_mfma_f32_16x16x32_bf16 v[134:137], v[4:7], v[36:39], 0
	v_mfma_f32_16x16x32_bf16 v[144:147], v[4:7], v[52:55], 0
	v_mfma_f32_16x16x32_bf16 v[152:155], v[4:7], v[116:119], 0
	v_mfma_f32_16x16x32_bf16 v[4:7], v[4:7], v[124:127], 0
	v_mfma_f32_16x16x32_bf16 v[140:143], v[12:15], v[36:39], 0
	v_mfma_f32_16x16x32_bf16 v[148:151], v[12:15], v[52:55], 0
	v_mfma_f32_16x16x32_bf16 v[156:159], v[12:15], v[116:119], 0
	v_mfma_f32_16x16x32_bf16 v[160:163], v[8:11], v[128:131], v[4:7]
	v_mfma_f32_16x16x32_bf16 v[4:7], v[12:15], v[124:127], 0
	v_mfma_f32_16x16x32_bf16 v[136:139], v[8:11], v[44:47], v[134:137]
	v_mfma_f32_16x16x32_bf16 v[140:143], v[16:19], v[44:47], v[140:143]
	v_mfma_f32_16x16x32_bf16 v[144:147], v[8:11], v[60:63], v[144:147]
	v_mfma_f32_16x16x32_bf16 v[148:151], v[16:19], v[60:63], v[148:151]
	v_mfma_f32_16x16x32_bf16 v[152:155], v[8:11], v[120:123], v[152:155]
	v_mfma_f32_16x16x32_bf16 v[156:159], v[16:19], v[120:123], v[156:159]
	v_mfma_f32_16x16x32_bf16 v[164:167], v[16:19], v[128:131], v[4:7]
	s_setprio 0
	s_setprio 1
	v_mfma_f32_16x16x32_bf16 v[4:7], v[20:23], v[36:39], 0
	v_mfma_f32_16x16x32_bf16 v[168:171], v[24:27], v[44:47], v[4:7]
	v_mfma_f32_16x16x32_bf16 v[4:7], v[28:31], v[36:39], 0
	v_mfma_f32_16x16x32_bf16 v[172:175], v[32:35], v[44:47], v[4:7]
	v_mfma_f32_16x16x32_bf16 v[4:7], v[20:23], v[52:55], 0
	v_mfma_f32_16x16x32_bf16 v[176:179], v[24:27], v[60:63], v[4:7]
	v_mfma_f32_16x16x32_bf16 v[4:7], v[28:31], v[52:55], 0
	v_mfma_f32_16x16x32_bf16 v[180:183], v[32:35], v[60:63], v[4:7]
	v_mfma_f32_16x16x32_bf16 v[4:7], v[20:23], v[116:119], 0
	v_mfma_f32_16x16x32_bf16 v[184:187], v[24:27], v[120:123], v[4:7]
	v_mfma_f32_16x16x32_bf16 v[4:7], v[28:31], v[116:119], 0
	v_mfma_f32_16x16x32_bf16 v[120:123], v[32:35], v[120:123], v[4:7]
	v_mfma_f32_16x16x32_bf16 v[4:7], v[20:23], v[124:127], 0
	v_mfma_f32_16x16x32_bf16 v[188:191], v[24:27], v[128:131], v[4:7]
	v_mfma_f32_16x16x32_bf16 v[4:7], v[28:31], v[124:127], 0
	v_mfma_f32_16x16x32_bf16 v[128:131], v[32:35], v[128:131], v[4:7]
	s_setprio 0
	s_barrier
	s_add_i32 s46, 0, 0x18000
	s_add_i32 s8, 0, 0x1c000
	v_add_u32_e32 v133, s46, v198
	v_add_u32_e32 v134, s8, v198
	ds_read_b128 v[116:119], v133
	ds_read_b128 v[124:127], v133 offset:1024
	ds_read_b128 v[202:205], v133 offset:2048
	ds_read_b128 v[220:223], v133 offset:3072
	ds_read_b128 v[224:227], v134
	ds_read_b128 v[228:231], v134 offset:1024
	ds_read_b128 v[232:235], v134 offset:2048
	ds_read_b128 v[236:239], v134 offset:3072
	s_mov_b32 m0, s84
	s_mov_b64 s[16:17], s[18:19]
	ds_read_b128 v[44:47], v199 offset:32768
	ds_read_b128 v[52:55], v199 offset:33792
	ds_read_b128 v[60:63], v199 offset:34816
	ds_read_b128 v[242:245], v199 offset:35840
	ds_read_b128 v[246:249], v199 offset:36864
	ds_read_b128 v[250:253], v199 offset:37888
	ds_read_b128 v[206:209], v199 offset:38912
	ds_read_b128 v[216:219], v199 offset:39936
	s_nop 0
	global_load_lds_dwordx4 v194, s[16:17]
	s_mov_b32 m0, s85
	s_nop 0
	global_load_lds_dwordx4 v195, s[16:17]
	s_add_u32 s16, s18, s52
	s_addc_u32 s17, s19, s53
	s_mov_b32 m0, s86
	s_nop 0
	global_load_lds_dwordx4 v194, s[16:17]
	s_mov_b32 m0, s87
	s_nop 0
	global_load_lds_dwordx4 v195, s[16:17]
	s_waitcnt vmcnt(8)
	s_waitcnt lgkmcnt(0)
	s_barrier
	s_setprio 1
	s_waitcnt lgkmcnt(0)
	v_mfma_f32_16x16x32_bf16 v[4:7], v[116:119], v[44:47], v[68:71]
	v_mfma_f32_16x16x32_bf16 v[4:7], v[124:127], v[52:55], v[4:7]
	v_mfma_f32_16x16x32_bf16 v[8:11], v[202:205], v[44:47], v[72:75]
	v_mfma_f32_16x16x32_bf16 v[8:11], v[220:223], v[52:55], v[8:11]
	v_mfma_f32_16x16x32_bf16 v[12:15], v[116:119], v[60:63], v[76:79]
	v_mfma_f32_16x16x32_bf16 v[12:15], v[124:127], v[242:245], v[12:15]
	v_mfma_f32_16x16x32_bf16 v[16:19], v[202:205], v[60:63], v[80:83]
	v_mfma_f32_16x16x32_bf16 v[16:19], v[220:223], v[242:245], v[16:19]
	v_mfma_f32_16x16x32_bf16 v[20:23], v[116:119], v[246:249], v[84:87]
	v_mfma_f32_16x16x32_bf16 v[20:23], v[124:127], v[250:253], v[20:23]
	v_mfma_f32_16x16x32_bf16 v[24:27], v[202:205], v[246:249], v[88:91]
	v_mfma_f32_16x16x32_bf16 v[24:27], v[220:223], v[250:253], v[24:27]
	v_mfma_f32_16x16x32_bf16 v[28:31], v[116:119], v[206:209], v[92:95]
	v_mfma_f32_16x16x32_bf16 v[28:31], v[124:127], v[216:219], v[28:31]
	v_mfma_f32_16x16x32_bf16 v[32:35], v[202:205], v[206:209], v[96:99]
	v_mfma_f32_16x16x32_bf16 v[32:35], v[220:223], v[216:219], v[32:35]
	s_setprio 0
	s_setprio 1
	v_mfma_f32_16x16x32_bf16 v[36:39], v[224:227], v[44:47], v[100:103]
	v_mfma_f32_16x16x32_bf16 v[40:43], v[232:235], v[44:47], v[40:43]
	v_mfma_f32_16x16x32_bf16 v[36:39], v[228:231], v[52:55], v[36:39]
	v_mfma_f32_16x16x32_bf16 v[40:43], v[236:239], v[52:55], v[40:43]
	v_mfma_f32_16x16x32_bf16 v[44:47], v[224:227], v[60:63], v[104:107]
	v_mfma_f32_16x16x32_bf16 v[48:51], v[232:235], v[60:63], v[48:51]
	v_mfma_f32_16x16x32_bf16 v[52:55], v[224:227], v[246:249], v[108:111]
	v_mfma_f32_16x16x32_bf16 v[56:59], v[232:235], v[246:249], v[56:59]
	v_mfma_f32_16x16x32_bf16 v[60:63], v[224:227], v[206:209], v[112:115]
	v_mfma_f32_16x16x32_bf16 v[64:67], v[232:235], v[206:209], v[64:67]
	v_mfma_f32_16x16x32_bf16 v[44:47], v[228:231], v[242:245], v[44:47]
	v_mfma_f32_16x16x32_bf16 v[48:51], v[236:239], v[242:245], v[48:51]
	v_mfma_f32_16x16x32_bf16 v[52:55], v[228:231], v[250:253], v[52:55]
	v_mfma_f32_16x16x32_bf16 v[56:59], v[236:239], v[250:253], v[56:59]
	v_mfma_f32_16x16x32_bf16 v[60:63], v[228:231], v[216:219], v[60:63]
	v_mfma_f32_16x16x32_bf16 v[64:67], v[236:239], v[216:219], v[64:67]
	s_setprio 0
	s_barrier
	s_add_i32 s46, s46, s82
	s_mov_b64 s[16:17], s[28:29]
	s_mov_b32 m0, s46
	s_add_i32 s47, s46, 0x2000
	ds_read_b128 v[104:107], v199 offset:49152
	ds_read_b128 v[108:111], v199 offset:50176
	ds_read_b128 v[112:115], v199 offset:51200
	ds_read_b128 v[206:209], v199 offset:52224
	ds_read_b128 v[216:219], v199 offset:53248
	ds_read_b128 v[242:245], v199 offset:54272
	ds_read_b128 v[246:249], v199 offset:55296
	ds_read_b128 v[250:253], v199 offset:56320
	s_nop 0
	global_load_lds_dwordx4 v201, s[16:17]
	s_mov_b32 m0, s47
	s_nop 0
	global_load_lds_dwordx4 v200, s[16:17]
	s_add_u32 s16, s28, s52
	s_addc_u32 s17, s29, s53
	s_add_i32 s28, s8, s82
	s_mov_b32 m0, s28
	s_add_i32 s29, s28, 0x2000
	s_nop 0
	global_load_lds_dwordx4 v201, s[16:17]
	s_mov_b32 m0, s29
	s_nop 0
	global_load_lds_dwordx4 v200, s[16:17]
	s_waitcnt vmcnt(6)
	s_waitcnt lgkmcnt(0)
	s_barrier
	s_setprio 1
	s_waitcnt lgkmcnt(0)
	v_mfma_f32_16x16x32_bf16 v[68:71], v[116:119], v[104:107], v[136:139]
	v_mfma_f32_16x16x32_bf16 v[68:71], v[124:127], v[108:111], v[68:71]
	v_mfma_f32_16x16x32_bf16 v[72:75], v[202:205], v[104:107], v[140:143]
	v_mfma_f32_16x16x32_bf16 v[72:75], v[220:223], v[108:111], v[72:75]
	v_mfma_f32_16x16x32_bf16 v[76:79], v[116:119], v[112:115], v[144:147]
	v_mfma_f32_16x16x32_bf16 v[76:79], v[124:127], v[206:209], v[76:79]
	v_mfma_f32_16x16x32_bf16 v[80:83], v[202:205], v[112:115], v[148:151]
	v_mfma_f32_16x16x32_bf16 v[80:83], v[220:223], v[206:209], v[80:83]
	v_mfma_f32_16x16x32_bf16 v[84:87], v[116:119], v[216:219], v[152:155]
	v_mfma_f32_16x16x32_bf16 v[84:87], v[124:127], v[242:245], v[84:87]
	v_mfma_f32_16x16x32_bf16 v[88:91], v[202:205], v[216:219], v[156:159]
	v_mfma_f32_16x16x32_bf16 v[88:91], v[220:223], v[242:245], v[88:91]
	v_mfma_f32_16x16x32_bf16 v[92:95], v[116:119], v[246:249], v[160:163]
	v_mfma_f32_16x16x32_bf16 v[92:95], v[124:127], v[250:253], v[92:95]
	v_mfma_f32_16x16x32_bf16 v[96:99], v[202:205], v[246:249], v[164:167]
	v_mfma_f32_16x16x32_bf16 v[96:99], v[220:223], v[250:253], v[96:99]
	s_setprio 0
	s_setprio 1
	v_mfma_f32_16x16x32_bf16 v[100:103], v[224:227], v[104:107], v[168:171]
	v_mfma_f32_16x16x32_bf16 v[104:107], v[232:235], v[104:107], v[172:175]
	v_mfma_f32_16x16x32_bf16 v[100:103], v[228:231], v[108:111], v[100:103]
	v_mfma_f32_16x16x32_bf16 v[104:107], v[236:239], v[108:111], v[104:107]
	v_mfma_f32_16x16x32_bf16 v[108:111], v[224:227], v[112:115], v[176:179]
	v_mfma_f32_16x16x32_bf16 v[112:115], v[232:235], v[112:115], v[180:183]
	v_mfma_f32_16x16x32_bf16 v[116:119], v[224:227], v[216:219], v[184:187]
	v_mfma_f32_16x16x32_bf16 v[120:123], v[232:235], v[216:219], v[120:123]
	v_mfma_f32_16x16x32_bf16 v[124:127], v[224:227], v[246:249], v[188:191]
	v_mfma_f32_16x16x32_bf16 v[128:131], v[232:235], v[246:249], v[128:131]
	v_mfma_f32_16x16x32_bf16 v[108:111], v[228:231], v[206:209], v[108:111]
	v_mfma_f32_16x16x32_bf16 v[112:115], v[236:239], v[206:209], v[112:115]
	v_mfma_f32_16x16x32_bf16 v[116:119], v[228:231], v[242:245], v[116:119]
	v_mfma_f32_16x16x32_bf16 v[120:123], v[236:239], v[242:245], v[120:123]
	v_mfma_f32_16x16x32_bf16 v[124:127], v[228:231], v[250:253], v[124:127]
	v_mfma_f32_16x16x32_bf16 v[128:131], v[236:239], v[250:253], v[128:131]
	s_setprio 0
	s_barrier
	s_andn2_b64 vcc, exec, s[64:65]
	s_cbranch_vccnz .LBB0_431
	s_add_u32 s48, s20, 0x200
	s_addc_u32 s49, s21, 0
	s_add_u32 s26, s26, 0x200
	s_addc_u32 s27, s27, 0
	s_mov_b32 s66, 4
	.p2align	6
	s_nop 0
	s_nop 0
	s_nop 0
	s_nop 0
	s_nop 0
	s_nop 0
	s_nop 0
	s_nop 0
	s_nop 0
	s_nop 0
	s_nop 0
	s_nop 0

.LBB0_720:
	s_add_i32 s84, s84, 2
	s_and_b64 s[8:9], s[30:31], exec
	s_cselect_b32 s9, s39, s83
	s_cselect_b32 s8, s38, s82
	s_add_u32 s16, s28, 0x80
	v_mov_b32_e32 v197, v3
	v_mov_b32_e32 v201, v3
	v_mov_b32_e32 v199, v3
	s_addc_u32 s17, s29, 0
	s_setprio 0
	s_barrier
	s_add_i32 s28, 0, 0x18000
	s_add_i32 s29, 0, 0x1c000
	v_add_u32_e32 v144, s28, v204
	v_add_u32_e32 v160, s29, v204
	ds_read_b128 v[132:135], v144
	ds_read_b128 v[136:139], v144 offset:1024
	ds_read_b128 v[140:143], v144 offset:2048
	ds_read_b128 v[144:147], v144 offset:3072
	ds_read_b128 v[148:151], v160
	ds_read_b128 v[152:155], v160 offset:1024
	ds_read_b128 v[156:159], v160 offset:2048
	ds_read_b128 v[160:163], v160 offset:3072
	s_mov_b64 s[26:27], s[8:9]
	s_mov_b32 m0, s56
	s_waitcnt lgkmcnt(0)
	ds_read_b128 v[164:167], v205 offset:40960
	ds_read_b128 v[168:171], v205 offset:41984
	ds_read_b128 v[172:175], v205 offset:43008
	ds_read_b128 v[176:179], v205 offset:44032
	ds_read_b128 v[180:183], v205 offset:45056
	ds_read_b128 v[184:187], v205 offset:46080
	ds_read_b128 v[188:191], v205 offset:47104
	ds_read_b128 v[192:195], v205 offset:48128
	s_add_u32 s8, s8, s14
	v_lshl_add_u64 v[206:207], s[26:27], 0, v[2:3]
	global_load_lds_dwordx4 v[206:207], off
	v_lshl_add_u64 v[206:207], s[26:27], 0, v[196:197]
	s_mov_b32 m0, s61
	s_addc_u32 s9, s9, s15
	global_load_lds_dwordx4 v[206:207], off
	s_mov_b32 m0, s62
	v_lshl_add_u64 v[206:207], s[8:9], 0, v[2:3]
	global_load_lds_dwordx4 v[206:207], off
	v_lshl_add_u64 v[206:207], s[8:9], 0, v[196:197]
	s_mov_b32 m0, s63
	s_nop 0
	global_load_lds_dwordx4 v[206:207], off
	s_waitcnt vmcnt(8)
	s_waitcnt lgkmcnt(0)
	s_barrier
	s_setprio 1
	s_waitcnt lgkmcnt(0)
	v_mfma_f32_16x16x32_bf16 v[128:131], v[132:135], v[164:167], v[128:131]
	v_mfma_f32_16x16x32_bf16 v[128:131], v[136:139], v[168:171], v[128:131]
	v_mfma_f32_16x16x32_bf16 v[124:127], v[140:143], v[164:167], v[124:127]
	v_mfma_f32_16x16x32_bf16 v[124:127], v[144:147], v[168:171], v[124:127]
	v_mfma_f32_16x16x32_bf16 v[120:123], v[132:135], v[172:175], v[120:123]
	v_mfma_f32_16x16x32_bf16 v[120:123], v[136:139], v[176:179], v[120:123]
	v_mfma_f32_16x16x32_bf16 v[116:119], v[140:143], v[172:175], v[116:119]
	v_mfma_f32_16x16x32_bf16 v[116:119], v[144:147], v[176:179], v[116:119]
	v_mfma_f32_16x16x32_bf16 v[112:115], v[132:135], v[180:183], v[112:115]
	v_mfma_f32_16x16x32_bf16 v[112:115], v[136:139], v[184:187], v[112:115]
	v_mfma_f32_16x16x32_bf16 v[108:111], v[140:143], v[180:183], v[108:111]
	v_mfma_f32_16x16x32_bf16 v[108:111], v[144:147], v[184:187], v[108:111]
	v_mfma_f32_16x16x32_bf16 v[104:107], v[132:135], v[188:191], v[104:107]
	v_mfma_f32_16x16x32_bf16 v[104:107], v[136:139], v[192:195], v[104:107]
	v_mfma_f32_16x16x32_bf16 v[100:103], v[140:143], v[188:191], v[100:103]
	v_mfma_f32_16x16x32_bf16 v[100:103], v[144:147], v[192:195], v[100:103]
	s_setprio 0
	s_setprio 1
	v_mfma_f32_16x16x32_bf16 v[96:99], v[148:151], v[164:167], v[96:99]
	v_mfma_f32_16x16x32_bf16 v[96:99], v[152:155], v[168:171], v[96:99]
	v_mfma_f32_16x16x32_bf16 v[92:95], v[156:159], v[164:167], v[92:95]
	v_mfma_f32_16x16x32_bf16 v[92:95], v[160:163], v[168:171], v[92:95]
	v_mfma_f32_16x16x32_bf16 v[88:91], v[148:151], v[172:175], v[88:91]
	v_mfma_f32_16x16x32_bf16 v[88:91], v[152:155], v[176:179], v[88:91]
	v_mfma_f32_16x16x32_bf16 v[84:87], v[156:159], v[172:175], v[84:87]
	v_mfma_f32_16x16x32_bf16 v[84:87], v[160:163], v[176:179], v[84:87]
	v_mfma_f32_16x16x32_bf16 v[80:83], v[148:151], v[180:183], v[80:83]
	v_mfma_f32_16x16x32_bf16 v[80:83], v[152:155], v[184:187], v[80:83]
	v_mfma_f32_16x16x32_bf16 v[76:79], v[156:159], v[180:183], v[76:79]
	v_mfma_f32_16x16x32_bf16 v[76:79], v[160:163], v[184:187], v[76:79]
	v_mfma_f32_16x16x32_bf16 v[72:75], v[148:151], v[188:191], v[72:75]
	v_mfma_f32_16x16x32_bf16 v[72:75], v[152:155], v[192:195], v[72:75]
	v_mfma_f32_16x16x32_bf16 v[68:71], v[156:159], v[188:191], v[68:71]
	v_mfma_f32_16x16x32_bf16 v[68:71], v[160:163], v[192:195], v[68:71]
	s_setprio 0
	s_barrier
	s_mov_b64 s[8:9], s[16:17]
	s_add_i32 s26, s28, s55
	ds_read_b128 v[164:167], v205 offset:57344
	ds_read_b128 v[168:171], v205 offset:58368
	ds_read_b128 v[172:175], v205 offset:59392
	ds_read_b128 v[176:179], v205 offset:60416
	ds_read_b128 v[180:183], v205 offset:61440
	ds_read_b128 v[184:187], v205 offset:62464
	ds_read_b128 v[188:191], v205 offset:63488
	ds_read_b128 v[192:195], v205 offset:64512
	s_mov_b32 m0, s26
	v_lshl_add_u64 v[206:207], s[8:9], 0, v[200:201]
	global_load_lds_dwordx4 v[206:207], off
	s_add_i32 m0, s26, 0x2000
	v_lshl_add_u64 v[206:207], s[8:9], 0, v[198:199]
	s_add_u32 s8, s16, s14
	s_addc_u32 s9, s17, s15
	s_add_i32 s16, s29, s55
	global_load_lds_dwordx4 v[206:207], off
	s_mov_b32 m0, s16
	v_lshl_add_u64 v[206:207], s[8:9], 0, v[200:201]
	global_load_lds_dwordx4 v[206:207], off
	v_lshl_add_u64 v[206:207], s[8:9], 0, v[198:199]
	s_add_i32 m0, s16, 0x2000
	s_nop 0
	global_load_lds_dwordx4 v[206:207], off
	s_waitcnt vmcnt(6)
	s_waitcnt lgkmcnt(0)
	s_barrier
	s_setprio 1
	s_waitcnt lgkmcnt(0)
	v_mfma_f32_16x16x32_bf16 v[64:67], v[132:135], v[164:167], v[64:67]
	v_mfma_f32_16x16x32_bf16 v[64:67], v[136:139], v[168:171], v[64:67]
	v_mfma_f32_16x16x32_bf16 v[60:63], v[140:143], v[164:167], v[60:63]
	v_mfma_f32_16x16x32_bf16 v[60:63], v[144:147], v[168:171], v[60:63]
	v_mfma_f32_16x16x32_bf16 v[56:59], v[132:135], v[172:175], v[56:59]
	v_mfma_f32_16x16x32_bf16 v[56:59], v[136:139], v[176:179], v[56:59]
	v_mfma_f32_16x16x32_bf16 v[52:55], v[140:143], v[172:175], v[52:55]
	v_mfma_f32_16x16x32_bf16 v[52:55], v[144:147], v[176:179], v[52:55]
	v_mfma_f32_16x16x32_bf16 v[48:51], v[132:135], v[180:183], v[48:51]
	v_mfma_f32_16x16x32_bf16 v[48:51], v[136:139], v[184:187], v[48:51]
	v_mfma_f32_16x16x32_bf16 v[44:47], v[140:143], v[180:183], v[44:47]
	v_mfma_f32_16x16x32_bf16 v[44:47], v[144:147], v[184:187], v[44:47]
	v_mfma_f32_16x16x32_bf16 v[40:43], v[132:135], v[188:191], v[40:43]
	v_mfma_f32_16x16x32_bf16 v[40:43], v[136:139], v[192:195], v[40:43]
	v_mfma_f32_16x16x32_bf16 v[36:39], v[140:143], v[188:191], v[36:39]
	v_mfma_f32_16x16x32_bf16 v[36:39], v[144:147], v[192:195], v[36:39]
	s_setprio 0
	s_setprio 1
	v_mfma_f32_16x16x32_bf16 v[32:35], v[148:151], v[164:167], v[32:35]
	v_mfma_f32_16x16x32_bf16 v[32:35], v[152:155], v[168:171], v[32:35]
	v_mfma_f32_16x16x32_bf16 v[28:31], v[156:159], v[164:167], v[28:31]
	v_mfma_f32_16x16x32_bf16 v[28:31], v[160:163], v[168:171], v[28:31]
	v_mfma_f32_16x16x32_bf16 v[24:27], v[148:151], v[172:175], v[24:27]
	v_mfma_f32_16x16x32_bf16 v[24:27], v[152:155], v[176:179], v[24:27]
	v_mfma_f32_16x16x32_bf16 v[20:23], v[156:159], v[172:175], v[20:23]
	v_mfma_f32_16x16x32_bf16 v[20:23], v[160:163], v[176:179], v[20:23]
	v_mfma_f32_16x16x32_bf16 v[16:19], v[148:151], v[180:183], v[16:19]
	v_mfma_f32_16x16x32_bf16 v[16:19], v[152:155], v[184:187], v[16:19]
	v_mfma_f32_16x16x32_bf16 v[12:15], v[156:159], v[180:183], v[12:15]
	v_mfma_f32_16x16x32_bf16 v[12:15], v[160:163], v[184:187], v[12:15]
	v_mfma_f32_16x16x32_bf16 v[8:11], v[148:151], v[188:191], v[8:11]
	v_mfma_f32_16x16x32_bf16 v[8:11], v[152:155], v[192:195], v[8:11]
	v_mfma_f32_16x16x32_bf16 v[4:7], v[156:159], v[188:191], v[4:7]
	v_mfma_f32_16x16x32_bf16 v[4:7], v[160:163], v[192:195], v[4:7]
	s_setprio 0
	s_barrier
	s_add_u32 s80, s80, 0x100
	s_addc_u32 s81, s81, 0
	s_add_u32 s82, s82, 0x100
	s_addc_u32 s83, s83, 0
	s_cmp_ge_u32 s84, s47
	s_cbranch_scc1 .LBB0_737
	.p2align	6
	s_nop 0
	s_nop 0
	s_nop 0
	s_nop 0
	s_nop 0
	s_nop 0
	s_nop 0
	s_nop 0
	s_nop 0
	s_nop 0
	s_nop 0
	s_nop 0

.LBB0_760:
	s_add_i32 s80, s80, 2
	s_and_b64 s[8:9], s[30:31], exec
	s_cselect_b32 s9, s39, s79
	s_cselect_b32 s8, s38, s78
	s_add_u32 s16, s28, 0x80
	v_mov_b32_e32 v197, v3
	v_mov_b32_e32 v201, v3
	v_mov_b32_e32 v199, v3
	s_addc_u32 s17, s29, 0
	s_setprio 0
	s_barrier
	s_add_i32 s28, 0, 0x18000
	s_add_i32 s29, 0, 0x1c000
	v_add_u32_e32 v144, s28, v204
	v_add_u32_e32 v160, s29, v204
	ds_read_b128 v[132:135], v144
	ds_read_b128 v[136:139], v144 offset:1024
	ds_read_b128 v[140:143], v144 offset:2048
	ds_read_b128 v[144:147], v144 offset:3072
	ds_read_b128 v[148:151], v160
	ds_read_b128 v[152:155], v160 offset:1024
	ds_read_b128 v[156:159], v160 offset:2048
	ds_read_b128 v[160:163], v160 offset:3072
	s_mov_b64 s[26:27], s[8:9]
	s_mov_b32 m0, s56
	s_waitcnt lgkmcnt(0)
	ds_read_b128 v[164:167], v205 offset:32768
	ds_read_b128 v[168:171], v205 offset:33792
	ds_read_b128 v[172:175], v205 offset:34816
	ds_read_b128 v[176:179], v205 offset:35840
	ds_read_b128 v[180:183], v205 offset:36864
	ds_read_b128 v[184:187], v205 offset:37888
	ds_read_b128 v[188:191], v205 offset:38912
	ds_read_b128 v[192:195], v205 offset:39936
	s_add_u32 s8, s8, s14
	v_lshl_add_u64 v[206:207], s[26:27], 0, v[2:3]
	global_load_lds_dwordx4 v[206:207], off
	v_lshl_add_u64 v[206:207], s[26:27], 0, v[196:197]
	s_mov_b32 m0, s61
	s_addc_u32 s9, s9, s15
	global_load_lds_dwordx4 v[206:207], off
	s_mov_b32 m0, s62
	v_lshl_add_u64 v[206:207], s[8:9], 0, v[2:3]
	global_load_lds_dwordx4 v[206:207], off
	v_lshl_add_u64 v[206:207], s[8:9], 0, v[196:197]
	s_mov_b32 m0, s63
	s_nop 0
	global_load_lds_dwordx4 v[206:207], off
	s_waitcnt vmcnt(8)
	s_waitcnt lgkmcnt(0)
	s_barrier
	s_setprio 1
	s_waitcnt lgkmcnt(0)
	v_mfma_f32_16x16x32_bf16 v[128:131], v[132:135], v[164:167], v[128:131]
	v_mfma_f32_16x16x32_bf16 v[128:131], v[136:139], v[168:171], v[128:131]
	v_mfma_f32_16x16x32_bf16 v[124:127], v[140:143], v[164:167], v[124:127]
	v_mfma_f32_16x16x32_bf16 v[124:127], v[144:147], v[168:171], v[124:127]
	v_mfma_f32_16x16x32_bf16 v[120:123], v[132:135], v[172:175], v[120:123]
	v_mfma_f32_16x16x32_bf16 v[120:123], v[136:139], v[176:179], v[120:123]
	v_mfma_f32_16x16x32_bf16 v[116:119], v[140:143], v[172:175], v[116:119]
	v_mfma_f32_16x16x32_bf16 v[116:119], v[144:147], v[176:179], v[116:119]
	v_mfma_f32_16x16x32_bf16 v[112:115], v[132:135], v[180:183], v[112:115]
	v_mfma_f32_16x16x32_bf16 v[112:115], v[136:139], v[184:187], v[112:115]
	v_mfma_f32_16x16x32_bf16 v[108:111], v[140:143], v[180:183], v[108:111]
	v_mfma_f32_16x16x32_bf16 v[108:111], v[144:147], v[184:187], v[108:111]
	v_mfma_f32_16x16x32_bf16 v[104:107], v[132:135], v[188:191], v[104:107]
	v_mfma_f32_16x16x32_bf16 v[104:107], v[136:139], v[192:195], v[104:107]
	v_mfma_f32_16x16x32_bf16 v[100:103], v[140:143], v[188:191], v[100:103]
	v_mfma_f32_16x16x32_bf16 v[100:103], v[144:147], v[192:195], v[100:103]
	s_setprio 0
	s_setprio 1
	v_mfma_f32_16x16x32_bf16 v[96:99], v[148:151], v[164:167], v[96:99]
	v_mfma_f32_16x16x32_bf16 v[96:99], v[152:155], v[168:171], v[96:99]
	v_mfma_f32_16x16x32_bf16 v[92:95], v[156:159], v[164:167], v[92:95]
	v_mfma_f32_16x16x32_bf16 v[92:95], v[160:163], v[168:171], v[92:95]
	v_mfma_f32_16x16x32_bf16 v[88:91], v[148:151], v[172:175], v[88:91]
	v_mfma_f32_16x16x32_bf16 v[88:91], v[152:155], v[176:179], v[88:91]
	v_mfma_f32_16x16x32_bf16 v[84:87], v[156:159], v[172:175], v[84:87]
	v_mfma_f32_16x16x32_bf16 v[84:87], v[160:163], v[176:179], v[84:87]
	v_mfma_f32_16x16x32_bf16 v[80:83], v[148:151], v[180:183], v[80:83]
	v_mfma_f32_16x16x32_bf16 v[80:83], v[152:155], v[184:187], v[80:83]
	v_mfma_f32_16x16x32_bf16 v[76:79], v[156:159], v[180:183], v[76:79]
	v_mfma_f32_16x16x32_bf16 v[76:79], v[160:163], v[184:187], v[76:79]
	v_mfma_f32_16x16x32_bf16 v[72:75], v[148:151], v[188:191], v[72:75]
	v_mfma_f32_16x16x32_bf16 v[72:75], v[152:155], v[192:195], v[72:75]
	v_mfma_f32_16x16x32_bf16 v[68:71], v[156:159], v[188:191], v[68:71]
	v_mfma_f32_16x16x32_bf16 v[68:71], v[160:163], v[192:195], v[68:71]
	s_setprio 0
	s_barrier
	s_mov_b64 s[8:9], s[16:17]
	s_add_i32 s26, s28, s55
	ds_read_b128 v[164:167], v205 offset:49152
	ds_read_b128 v[168:171], v205 offset:50176
	ds_read_b128 v[172:175], v205 offset:51200
	ds_read_b128 v[176:179], v205 offset:52224
	ds_read_b128 v[180:183], v205 offset:53248
	ds_read_b128 v[184:187], v205 offset:54272
	ds_read_b128 v[188:191], v205 offset:55296
	ds_read_b128 v[192:195], v205 offset:56320
	s_mov_b32 m0, s26
	v_lshl_add_u64 v[206:207], s[8:9], 0, v[200:201]
	global_load_lds_dwordx4 v[206:207], off
	s_add_i32 m0, s26, 0x2000
	v_lshl_add_u64 v[206:207], s[8:9], 0, v[198:199]
	s_add_u32 s8, s16, s14
	s_addc_u32 s9, s17, s15
	s_add_i32 s16, s29, s55
	global_load_lds_dwordx4 v[206:207], off
	s_mov_b32 m0, s16
	v_lshl_add_u64 v[206:207], s[8:9], 0, v[200:201]
	global_load_lds_dwordx4 v[206:207], off
	v_lshl_add_u64 v[206:207], s[8:9], 0, v[198:199]
	s_add_i32 m0, s16, 0x2000
	s_nop 0
	global_load_lds_dwordx4 v[206:207], off
	s_waitcnt vmcnt(6)
	s_waitcnt lgkmcnt(0)
	s_barrier
	s_setprio 1
	s_waitcnt lgkmcnt(0)
	v_mfma_f32_16x16x32_bf16 v[64:67], v[132:135], v[164:167], v[64:67]
	v_mfma_f32_16x16x32_bf16 v[64:67], v[136:139], v[168:171], v[64:67]
	v_mfma_f32_16x16x32_bf16 v[60:63], v[140:143], v[164:167], v[60:63]
	v_mfma_f32_16x16x32_bf16 v[60:63], v[144:147], v[168:171], v[60:63]
	v_mfma_f32_16x16x32_bf16 v[56:59], v[132:135], v[172:175], v[56:59]
	v_mfma_f32_16x16x32_bf16 v[56:59], v[136:139], v[176:179], v[56:59]
	v_mfma_f32_16x16x32_bf16 v[52:55], v[140:143], v[172:175], v[52:55]
	v_mfma_f32_16x16x32_bf16 v[52:55], v[144:147], v[176:179], v[52:55]
	v_mfma_f32_16x16x32_bf16 v[48:51], v[132:135], v[180:183], v[48:51]
	v_mfma_f32_16x16x32_bf16 v[48:51], v[136:139], v[184:187], v[48:51]
	v_mfma_f32_16x16x32_bf16 v[44:47], v[140:143], v[180:183], v[44:47]
	v_mfma_f32_16x16x32_bf16 v[44:47], v[144:147], v[184:187], v[44:47]
	v_mfma_f32_16x16x32_bf16 v[40:43], v[132:135], v[188:191], v[40:43]
	v_mfma_f32_16x16x32_bf16 v[40:43], v[136:139], v[192:195], v[40:43]
	v_mfma_f32_16x16x32_bf16 v[36:39], v[140:143], v[188:191], v[36:39]
	v_mfma_f32_16x16x32_bf16 v[36:39], v[144:147], v[192:195], v[36:39]
	s_setprio 0
	s_setprio 1
	v_mfma_f32_16x16x32_bf16 v[32:35], v[148:151], v[164:167], v[32:35]
	v_mfma_f32_16x16x32_bf16 v[32:35], v[152:155], v[168:171], v[32:35]
	v_mfma_f32_16x16x32_bf16 v[28:31], v[156:159], v[164:167], v[28:31]
	v_mfma_f32_16x16x32_bf16 v[28:31], v[160:163], v[168:171], v[28:31]
	v_mfma_f32_16x16x32_bf16 v[24:27], v[148:151], v[172:175], v[24:27]
	v_mfma_f32_16x16x32_bf16 v[24:27], v[152:155], v[176:179], v[24:27]
	v_mfma_f32_16x16x32_bf16 v[20:23], v[156:159], v[172:175], v[20:23]
	v_mfma_f32_16x16x32_bf16 v[20:23], v[160:163], v[176:179], v[20:23]
	v_mfma_f32_16x16x32_bf16 v[16:19], v[148:151], v[180:183], v[16:19]
	v_mfma_f32_16x16x32_bf16 v[16:19], v[152:155], v[184:187], v[16:19]
	v_mfma_f32_16x16x32_bf16 v[12:15], v[156:159], v[180:183], v[12:15]
	v_mfma_f32_16x16x32_bf16 v[12:15], v[160:163], v[184:187], v[12:15]
	v_mfma_f32_16x16x32_bf16 v[8:11], v[148:151], v[188:191], v[8:11]
	v_mfma_f32_16x16x32_bf16 v[8:11], v[152:155], v[192:195], v[8:11]
	v_mfma_f32_16x16x32_bf16 v[4:7], v[156:159], v[188:191], v[4:7]
	v_mfma_f32_16x16x32_bf16 v[4:7], v[160:163], v[192:195], v[4:7]
	s_setprio 0
	s_barrier
	s_add_u32 s76, s76, 0x100
	s_addc_u32 s77, s77, 0
	s_add_u32 s78, s78, 0x100
	s_addc_u32 s79, s79, 0
	s_cmp_ge_u32 s80, s47
	s_cbranch_scc1 .LBB0_777
	.p2align	6
	s_nop 0
	s_nop 0
	s_nop 0
	s_nop 0
	s_nop 0
	s_nop 0
	s_nop 0
	s_nop 0
	s_nop 0
	s_nop 0
	s_nop 0
	s_nop 0

.LBB0_853:
	s_add_u32 s16, s26, 0x100
	s_addc_u32 s17, s27, 0
	s_add_u32 s18, s20, 0x100
	s_addc_u32 s19, s21, 0
	s_and_b64 s[8:9], s[52:53], exec
	s_cselect_b32 s31, s41, s19
	s_cselect_b32 s30, s40, s18
	s_add_i32 s84, 0, 0x10000
	s_and_b64 s[8:9], s[52:53], exec
	s_cselect_b32 s19, s59, s17
	s_cselect_b32 s18, s58, s16
	s_add_i32 s86, 0, 0x14000
	v_add_u32_e32 v132, s84, v245
	v_add_u32_e32 v133, s86, v245
	ds_read_b128 v[4:7], v132
	ds_read_b128 v[8:11], v132 offset:1024
	ds_read_b128 v[12:15], v132 offset:2048
	ds_read_b128 v[16:19], v132 offset:3072
	ds_read_b128 v[20:23], v133
	ds_read_b128 v[24:27], v133 offset:1024
	ds_read_b128 v[28:31], v133 offset:2048
	ds_read_b128 v[32:35], v133 offset:3072
	s_add_u32 s8, s26, 0x80
	s_addc_u32 s9, s27, 0
	s_add_i32 s80, s7, 0x8000
	s_add_i32 s81, s7, 0xa000
	s_mov_b64 s[16:17], s[8:9]
	s_mov_b32 m0, s80
	s_add_u32 s8, s8, s42
	ds_read_b128 v[36:39], v246 offset:8192
	ds_read_b128 v[40:43], v246 offset:9216
	ds_read_b128 v[44:47], v246 offset:10240
	ds_read_b128 v[48:51], v246 offset:11264
	ds_read_b128 v[52:55], v246 offset:12288
	ds_read_b128 v[56:59], v246 offset:13312
	ds_read_b128 v[60:63], v246 offset:14336
	ds_read_b128 v[64:67], v246 offset:15360
	s_addc_u32 s9, s9, s43
	global_load_lds_dwordx4 v242, s[16:17]
	s_mov_b32 m0, s81
	s_add_i32 s82, s7, 0xc000
	global_load_lds_dwordx4 v2, s[16:17]
	s_mov_b32 m0, s82
	s_add_i32 s83, s7, 0xe000
	s_add_u32 s28, s30, 0x80
	global_load_lds_dwordx4 v242, s[8:9]
	s_mov_b32 m0, s83
	s_addc_u32 s29, s31, 0
	global_load_lds_dwordx4 v2, s[8:9]
	s_waitcnt vmcnt(8)
	s_waitcnt lgkmcnt(0)
	s_barrier
	s_setprio 1
	s_waitcnt lgkmcnt(0)
	v_mfma_f32_16x16x32_bf16 v[68:71], v[4:7], v[36:39], 0
	v_mfma_f32_16x16x32_bf16 v[72:75], v[12:15], v[36:39], 0
	v_mfma_f32_16x16x32_bf16 v[76:79], v[4:7], v[44:47], 0
	v_mfma_f32_16x16x32_bf16 v[80:83], v[12:15], v[44:47], 0
	v_mfma_f32_16x16x32_bf16 v[84:87], v[4:7], v[52:55], 0
	v_mfma_f32_16x16x32_bf16 v[88:91], v[12:15], v[52:55], 0
	v_mfma_f32_16x16x32_bf16 v[92:95], v[4:7], v[60:63], 0
	v_mfma_f32_16x16x32_bf16 v[96:99], v[12:15], v[60:63], 0
	v_mfma_f32_16x16x32_bf16 v[68:71], v[8:11], v[40:43], v[68:71]
	v_mfma_f32_16x16x32_bf16 v[72:75], v[16:19], v[40:43], v[72:75]
	v_mfma_f32_16x16x32_bf16 v[76:79], v[8:11], v[48:51], v[76:79]
	v_mfma_f32_16x16x32_bf16 v[80:83], v[16:19], v[48:51], v[80:83]
	v_mfma_f32_16x16x32_bf16 v[84:87], v[8:11], v[56:59], v[84:87]
	v_mfma_f32_16x16x32_bf16 v[88:91], v[16:19], v[56:59], v[88:91]
	v_mfma_f32_16x16x32_bf16 v[92:95], v[8:11], v[64:67], v[92:95]
	v_mfma_f32_16x16x32_bf16 v[96:99], v[16:19], v[64:67], v[96:99]
	s_setprio 0
	s_setprio 1
	v_mfma_f32_16x16x32_bf16 v[100:103], v[20:23], v[36:39], 0
	v_mfma_f32_16x16x32_bf16 v[36:39], v[28:31], v[36:39], 0
	v_mfma_f32_16x16x32_bf16 v[100:103], v[24:27], v[40:43], v[100:103]
	v_mfma_f32_16x16x32_bf16 v[40:43], v[32:35], v[40:43], v[36:39]
	v_mfma_f32_16x16x32_bf16 v[36:39], v[20:23], v[44:47], 0
	v_mfma_f32_16x16x32_bf16 v[104:107], v[24:27], v[48:51], v[36:39]
	v_mfma_f32_16x16x32_bf16 v[36:39], v[28:31], v[44:47], 0
	v_mfma_f32_16x16x32_bf16 v[48:51], v[32:35], v[48:51], v[36:39]
	v_mfma_f32_16x16x32_bf16 v[36:39], v[20:23], v[52:55], 0
	v_mfma_f32_16x16x32_bf16 v[108:111], v[24:27], v[56:59], v[36:39]
	v_mfma_f32_16x16x32_bf16 v[36:39], v[28:31], v[52:55], 0
	v_mfma_f32_16x16x32_bf16 v[56:59], v[32:35], v[56:59], v[36:39]
	v_mfma_f32_16x16x32_bf16 v[36:39], v[20:23], v[60:63], 0
	v_mfma_f32_16x16x32_bf16 v[112:115], v[24:27], v[64:67], v[36:39]
	v_mfma_f32_16x16x32_bf16 v[36:39], v[28:31], v[60:63], 0
	v_mfma_f32_16x16x32_bf16 v[64:67], v[32:35], v[64:67], v[36:39]
	s_setprio 0
	s_barrier
	s_add_i32 s84, s84, s6
	s_mov_b64 s[8:9], s[30:31]
	s_mov_b32 m0, s84
	s_add_i32 s85, s84, 0x2000
	s_nop 0
	ds_read_b128 v[36:39], v246 offset:24576
	ds_read_b128 v[44:47], v246 offset:25600
	ds_read_b128 v[52:55], v246 offset:26624
	ds_read_b128 v[60:63], v246 offset:27648
	ds_read_b128 v[116:119], v246 offset:28672
	ds_read_b128 v[120:123], v246 offset:29696
	ds_read_b128 v[124:127], v246 offset:30720
	ds_read_b128 v[128:131], v246 offset:31744
	s_nop 0
	global_load_lds_dwordx4 v248, s[8:9]
	s_mov_b32 m0, s85
	s_nop 0
	global_load_lds_dwordx4 v247, s[8:9]
	s_add_u32 s8, s30, s42
	s_addc_u32 s9, s31, s43
	s_add_i32 s30, s86, s6
	s_mov_b32 m0, s30
	s_add_i32 s31, s30, 0x2000
	s_nop 0
	global_load_lds_dwordx4 v248, s[8:9]
	s_mov_b32 m0, s31
	s_nop 0
	global_load_lds_dwordx4 v247, s[8:9]
	s_waitcnt vmcnt(6)
	s_waitcnt lgkmcnt(0)
	s_barrier
	s_setprio 1
	s_waitcnt lgkmcnt(0)
	v_mfma_f32_16x16x32_bf16 v[134:137], v[4:7], v[36:39], 0
	v_mfma_f32_16x16x32_bf16 v[144:147], v[4:7], v[52:55], 0
	v_mfma_f32_16x16x32_bf16 v[152:155], v[4:7], v[116:119], 0
	v_mfma_f32_16x16x32_bf16 v[4:7], v[4:7], v[124:127], 0
	v_mfma_f32_16x16x32_bf16 v[140:143], v[12:15], v[36:39], 0
	v_mfma_f32_16x16x32_bf16 v[148:151], v[12:15], v[52:55], 0
	v_mfma_f32_16x16x32_bf16 v[156:159], v[12:15], v[116:119], 0
	v_mfma_f32_16x16x32_bf16 v[160:163], v[8:11], v[128:131], v[4:7]
	v_mfma_f32_16x16x32_bf16 v[4:7], v[12:15], v[124:127], 0
	v_mfma_f32_16x16x32_bf16 v[136:139], v[8:11], v[44:47], v[134:137]
	v_mfma_f32_16x16x32_bf16 v[140:143], v[16:19], v[44:47], v[140:143]
	v_mfma_f32_16x16x32_bf16 v[144:147], v[8:11], v[60:63], v[144:147]
	v_mfma_f32_16x16x32_bf16 v[148:151], v[16:19], v[60:63], v[148:151]
	v_mfma_f32_16x16x32_bf16 v[152:155], v[8:11], v[120:123], v[152:155]
	v_mfma_f32_16x16x32_bf16 v[156:159], v[16:19], v[120:123], v[156:159]
	v_mfma_f32_16x16x32_bf16 v[164:167], v[16:19], v[128:131], v[4:7]
	s_setprio 0
	s_setprio 1
	v_mfma_f32_16x16x32_bf16 v[4:7], v[20:23], v[36:39], 0
	v_mfma_f32_16x16x32_bf16 v[168:171], v[24:27], v[44:47], v[4:7]
	v_mfma_f32_16x16x32_bf16 v[4:7], v[28:31], v[36:39], 0
	v_mfma_f32_16x16x32_bf16 v[172:175], v[32:35], v[44:47], v[4:7]
	v_mfma_f32_16x16x32_bf16 v[4:7], v[20:23], v[52:55], 0
	v_mfma_f32_16x16x32_bf16 v[176:179], v[24:27], v[60:63], v[4:7]
	v_mfma_f32_16x16x32_bf16 v[4:7], v[28:31], v[52:55], 0
	v_mfma_f32_16x16x32_bf16 v[180:183], v[32:35], v[60:63], v[4:7]
	v_mfma_f32_16x16x32_bf16 v[4:7], v[20:23], v[116:119], 0
	v_mfma_f32_16x16x32_bf16 v[184:187], v[24:27], v[120:123], v[4:7]
	v_mfma_f32_16x16x32_bf16 v[4:7], v[28:31], v[116:119], 0
	v_mfma_f32_16x16x32_bf16 v[120:123], v[32:35], v[120:123], v[4:7]
	v_mfma_f32_16x16x32_bf16 v[4:7], v[20:23], v[124:127], 0
	v_mfma_f32_16x16x32_bf16 v[188:191], v[24:27], v[128:131], v[4:7]
	v_mfma_f32_16x16x32_bf16 v[4:7], v[28:31], v[124:127], 0
	v_mfma_f32_16x16x32_bf16 v[128:131], v[32:35], v[128:131], v[4:7]
	s_setprio 0
	s_barrier
	s_add_i32 s86, 0, 0x18000
	s_add_i32 s16, 0, 0x1c000
	v_add_u32_e32 v134, s86, v245
	v_add_u32_e32 v135, s16, v245
	ds_read_b128 v[116:119], v134
	ds_read_b128 v[124:127], v134 offset:1024
	ds_read_b128 v[192:195], v134 offset:2048
	ds_read_b128 v[196:199], v134 offset:3072
	ds_read_b128 v[200:203], v135
	ds_read_b128 v[204:207], v135 offset:1024
	ds_read_b128 v[216:219], v135 offset:2048
	ds_read_b128 v[220:223], v135 offset:3072
	s_mov_b32 m0, s7
	s_mov_b64 s[8:9], s[18:19]
	ds_read_b128 v[44:47], v246 offset:40960
	ds_read_b128 v[52:55], v246 offset:41984
	ds_read_b128 v[60:63], v246 offset:43008
	ds_read_b128 v[224:227], v246 offset:44032
	ds_read_b128 v[228:231], v246 offset:45056
	ds_read_b128 v[232:235], v246 offset:46080
	ds_read_b128 v[236:239], v246 offset:47104
	ds_read_b128 v[250:253], v246 offset:48128
	s_nop 0
	global_load_lds_dwordx4 v242, s[8:9]
	s_mov_b32 m0, s69
	s_nop 0
	global_load_lds_dwordx4 v2, s[8:9]
	s_add_u32 s8, s18, s42
	s_addc_u32 s9, s19, s43
	s_mov_b32 m0, s72
	s_nop 0
	global_load_lds_dwordx4 v242, s[8:9]
	s_mov_b32 m0, s73
	s_nop 0
	global_load_lds_dwordx4 v2, s[8:9]
	s_waitcnt vmcnt(8)
	s_waitcnt lgkmcnt(0)
	s_barrier
	s_setprio 1
	s_waitcnt lgkmcnt(0)
	v_mfma_f32_16x16x32_bf16 v[4:7], v[116:119], v[44:47], v[68:71]
	v_mfma_f32_16x16x32_bf16 v[4:7], v[124:127], v[52:55], v[4:7]
	v_mfma_f32_16x16x32_bf16 v[8:11], v[192:195], v[44:47], v[72:75]
	v_mfma_f32_16x16x32_bf16 v[8:11], v[196:199], v[52:55], v[8:11]
	v_mfma_f32_16x16x32_bf16 v[12:15], v[116:119], v[60:63], v[76:79]
	v_mfma_f32_16x16x32_bf16 v[12:15], v[124:127], v[224:227], v[12:15]
	v_mfma_f32_16x16x32_bf16 v[16:19], v[192:195], v[60:63], v[80:83]
	v_mfma_f32_16x16x32_bf16 v[16:19], v[196:199], v[224:227], v[16:19]
	v_mfma_f32_16x16x32_bf16 v[20:23], v[116:119], v[228:231], v[84:87]
	v_mfma_f32_16x16x32_bf16 v[20:23], v[124:127], v[232:235], v[20:23]
	v_mfma_f32_16x16x32_bf16 v[24:27], v[192:195], v[228:231], v[88:91]
	v_mfma_f32_16x16x32_bf16 v[24:27], v[196:199], v[232:235], v[24:27]
	v_mfma_f32_16x16x32_bf16 v[28:31], v[116:119], v[236:239], v[92:95]
	v_mfma_f32_16x16x32_bf16 v[28:31], v[124:127], v[250:253], v[28:31]
	v_mfma_f32_16x16x32_bf16 v[32:35], v[192:195], v[236:239], v[96:99]
	v_mfma_f32_16x16x32_bf16 v[32:35], v[196:199], v[250:253], v[32:35]
	s_setprio 0
	s_setprio 1
	v_mfma_f32_16x16x32_bf16 v[36:39], v[200:203], v[44:47], v[100:103]
	v_mfma_f32_16x16x32_bf16 v[40:43], v[216:219], v[44:47], v[40:43]
	v_mfma_f32_16x16x32_bf16 v[36:39], v[204:207], v[52:55], v[36:39]
	v_mfma_f32_16x16x32_bf16 v[40:43], v[220:223], v[52:55], v[40:43]
	v_mfma_f32_16x16x32_bf16 v[44:47], v[200:203], v[60:63], v[104:107]
	v_mfma_f32_16x16x32_bf16 v[48:51], v[216:219], v[60:63], v[48:51]
	v_mfma_f32_16x16x32_bf16 v[52:55], v[200:203], v[228:231], v[108:111]
	v_mfma_f32_16x16x32_bf16 v[56:59], v[216:219], v[228:231], v[56:59]
	v_mfma_f32_16x16x32_bf16 v[60:63], v[200:203], v[236:239], v[112:115]
	v_mfma_f32_16x16x32_bf16 v[64:67], v[216:219], v[236:239], v[64:67]
	v_mfma_f32_16x16x32_bf16 v[44:47], v[204:207], v[224:227], v[44:47]
	v_mfma_f32_16x16x32_bf16 v[48:51], v[220:223], v[224:227], v[48:51]
	v_mfma_f32_16x16x32_bf16 v[52:55], v[204:207], v[232:235], v[52:55]
	v_mfma_f32_16x16x32_bf16 v[56:59], v[220:223], v[232:235], v[56:59]
	v_mfma_f32_16x16x32_bf16 v[60:63], v[204:207], v[250:253], v[60:63]
	v_mfma_f32_16x16x32_bf16 v[64:67], v[220:223], v[250:253], v[64:67]
	s_setprio 0
	s_barrier
	s_add_i32 s86, s86, s6
	s_mov_b64 s[8:9], s[28:29]
	s_mov_b32 m0, s86
	s_add_i32 s87, s86, 0x2000
	ds_read_b128 v[104:107], v246 offset:57344
	ds_read_b128 v[108:111], v246 offset:58368
	ds_read_b128 v[112:115], v246 offset:59392
	ds_read_b128 v[224:227], v246 offset:60416
	ds_read_b128 v[228:231], v246 offset:61440
	ds_read_b128 v[232:235], v246 offset:62464
	ds_read_b128 v[236:239], v246 offset:63488
	ds_read_b128 v[250:253], v246 offset:64512
	s_nop 0
	global_load_lds_dwordx4 v248, s[8:9]
	s_mov_b32 m0, s87
	s_nop 0
	global_load_lds_dwordx4 v247, s[8:9]
	s_add_u32 s8, s28, s42
	s_addc_u32 s9, s29, s43
	s_add_i32 s28, s16, s6
	s_mov_b32 m0, s28
	s_add_i32 s29, s28, 0x2000
	s_nop 0
	global_load_lds_dwordx4 v248, s[8:9]
	s_mov_b32 m0, s29
	s_nop 0
	global_load_lds_dwordx4 v247, s[8:9]
	s_waitcnt vmcnt(6)
	s_waitcnt lgkmcnt(0)
	s_barrier
	s_setprio 1
	s_waitcnt lgkmcnt(0)
	v_mfma_f32_16x16x32_bf16 v[68:71], v[116:119], v[104:107], v[136:139]
	v_mfma_f32_16x16x32_bf16 v[68:71], v[124:127], v[108:111], v[68:71]
	v_mfma_f32_16x16x32_bf16 v[72:75], v[192:195], v[104:107], v[140:143]
	v_mfma_f32_16x16x32_bf16 v[72:75], v[196:199], v[108:111], v[72:75]
	v_mfma_f32_16x16x32_bf16 v[76:79], v[116:119], v[112:115], v[144:147]
	v_mfma_f32_16x16x32_bf16 v[76:79], v[124:127], v[224:227], v[76:79]
	v_mfma_f32_16x16x32_bf16 v[80:83], v[192:195], v[112:115], v[148:151]
	v_mfma_f32_16x16x32_bf16 v[80:83], v[196:199], v[224:227], v[80:83]
	v_mfma_f32_16x16x32_bf16 v[84:87], v[116:119], v[228:231], v[152:155]
	v_mfma_f32_16x16x32_bf16 v[84:87], v[124:127], v[232:235], v[84:87]
	v_mfma_f32_16x16x32_bf16 v[88:91], v[192:195], v[228:231], v[156:159]
	v_mfma_f32_16x16x32_bf16 v[88:91], v[196:199], v[232:235], v[88:91]
	v_mfma_f32_16x16x32_bf16 v[92:95], v[116:119], v[236:239], v[160:163]
	v_mfma_f32_16x16x32_bf16 v[92:95], v[124:127], v[250:253], v[92:95]
	v_mfma_f32_16x16x32_bf16 v[96:99], v[192:195], v[236:239], v[164:167]
	v_mfma_f32_16x16x32_bf16 v[96:99], v[196:199], v[250:253], v[96:99]
	s_setprio 0
	s_setprio 1
	v_mfma_f32_16x16x32_bf16 v[100:103], v[200:203], v[104:107], v[168:171]
	v_mfma_f32_16x16x32_bf16 v[104:107], v[216:219], v[104:107], v[172:175]
	v_mfma_f32_16x16x32_bf16 v[100:103], v[204:207], v[108:111], v[100:103]
	v_mfma_f32_16x16x32_bf16 v[104:107], v[220:223], v[108:111], v[104:107]
	v_mfma_f32_16x16x32_bf16 v[108:111], v[200:203], v[112:115], v[176:179]
	v_mfma_f32_16x16x32_bf16 v[112:115], v[216:219], v[112:115], v[180:183]
	v_mfma_f32_16x16x32_bf16 v[116:119], v[200:203], v[228:231], v[184:187]
	v_mfma_f32_16x16x32_bf16 v[120:123], v[216:219], v[228:231], v[120:123]
	v_mfma_f32_16x16x32_bf16 v[124:127], v[200:203], v[236:239], v[188:191]
	v_mfma_f32_16x16x32_bf16 v[128:131], v[216:219], v[236:239], v[128:131]
	v_mfma_f32_16x16x32_bf16 v[108:111], v[204:207], v[224:227], v[108:111]
	v_mfma_f32_16x16x32_bf16 v[112:115], v[220:223], v[224:227], v[112:115]
	v_mfma_f32_16x16x32_bf16 v[116:119], v[204:207], v[232:235], v[116:119]
	v_mfma_f32_16x16x32_bf16 v[120:123], v[220:223], v[232:235], v[120:123]
	v_mfma_f32_16x16x32_bf16 v[124:127], v[204:207], v[250:253], v[124:127]
	v_mfma_f32_16x16x32_bf16 v[128:131], v[220:223], v[250:253], v[128:131]
	s_setprio 0
	s_barrier
	s_andn2_b64 vcc, exec, s[54:55]
	s_cbranch_vccnz .LBB0_857
	s_add_u32 s88, s20, 0x200
	s_addc_u32 s89, s21, 0
	s_add_u32 s26, s26, 0x200
	s_addc_u32 s27, s27, 0
	s_mov_b32 s90, 4
	.p2align	6
	s_nop 0
	s_nop 0
	s_nop 0
	s_nop 0
	s_nop 0
	s_nop 0
	s_nop 0
	s_nop 0
	s_nop 0
	s_nop 0
	s_nop 0
	s_nop 0

.LBB0_878:
	s_add_u32 s16, s26, 0x100
	s_addc_u32 s17, s27, 0
	s_add_u32 s18, s20, 0x100
	s_addc_u32 s19, s21, 0
	s_and_b64 s[8:9], s[54:55], exec
	s_cselect_b32 s31, s43, s19
	s_cselect_b32 s30, s42, s18
	s_add_i32 s82, 0, 0x10000
	s_and_b64 s[8:9], s[54:55], exec
	s_cselect_b32 s19, s41, s17
	s_cselect_b32 s18, s40, s16
	s_add_i32 s84, 0, 0x14000
	v_add_u32_e32 v132, s82, v245
	v_add_u32_e32 v133, s84, v245
	ds_read_b128 v[4:7], v132
	ds_read_b128 v[8:11], v132 offset:1024
	ds_read_b128 v[12:15], v132 offset:2048
	ds_read_b128 v[16:19], v132 offset:3072
	ds_read_b128 v[20:23], v133
	ds_read_b128 v[24:27], v133 offset:1024
	ds_read_b128 v[28:31], v133 offset:2048
	ds_read_b128 v[32:35], v133 offset:3072
	s_add_u32 s8, s26, 0x80
	s_addc_u32 s9, s27, 0
	s_add_i32 s78, s7, 0x8000
	s_add_i32 s79, s7, 0xa000
	s_mov_b64 s[16:17], s[8:9]
	s_mov_b32 m0, s78
	s_add_u32 s8, s8, s46
	ds_read_b128 v[36:39], v246
	ds_read_b128 v[40:43], v246 offset:1024
	ds_read_b128 v[44:47], v246 offset:2048
	ds_read_b128 v[48:51], v246 offset:3072
	ds_read_b128 v[52:55], v246 offset:4096
	ds_read_b128 v[56:59], v246 offset:5120
	ds_read_b128 v[60:63], v246 offset:6144
	ds_read_b128 v[64:67], v246 offset:7168
	s_addc_u32 s9, s9, s47
	global_load_lds_dwordx4 v242, s[16:17]
	s_mov_b32 m0, s79
	s_add_i32 s80, s7, 0xc000
	global_load_lds_dwordx4 v2, s[16:17]
	s_mov_b32 m0, s80
	s_add_i32 s81, s7, 0xe000
	s_add_u32 s28, s30, 0x80
	global_load_lds_dwordx4 v242, s[8:9]
	s_mov_b32 m0, s81
	s_addc_u32 s29, s31, 0
	global_load_lds_dwordx4 v2, s[8:9]
	s_waitcnt vmcnt(8)
	s_waitcnt lgkmcnt(0)
	s_barrier
	s_setprio 1
	s_waitcnt lgkmcnt(0)
	v_mfma_f32_16x16x32_bf16 v[68:71], v[4:7], v[36:39], 0
	v_mfma_f32_16x16x32_bf16 v[72:75], v[12:15], v[36:39], 0
	v_mfma_f32_16x16x32_bf16 v[76:79], v[4:7], v[44:47], 0
	v_mfma_f32_16x16x32_bf16 v[80:83], v[12:15], v[44:47], 0
	v_mfma_f32_16x16x32_bf16 v[84:87], v[4:7], v[52:55], 0
	v_mfma_f32_16x16x32_bf16 v[88:91], v[12:15], v[52:55], 0
	v_mfma_f32_16x16x32_bf16 v[92:95], v[4:7], v[60:63], 0
	v_mfma_f32_16x16x32_bf16 v[96:99], v[12:15], v[60:63], 0
	v_mfma_f32_16x16x32_bf16 v[68:71], v[8:11], v[40:43], v[68:71]
	v_mfma_f32_16x16x32_bf16 v[72:75], v[16:19], v[40:43], v[72:75]
	v_mfma_f32_16x16x32_bf16 v[76:79], v[8:11], v[48:51], v[76:79]
	v_mfma_f32_16x16x32_bf16 v[80:83], v[16:19], v[48:51], v[80:83]
	v_mfma_f32_16x16x32_bf16 v[84:87], v[8:11], v[56:59], v[84:87]
	v_mfma_f32_16x16x32_bf16 v[88:91], v[16:19], v[56:59], v[88:91]
	v_mfma_f32_16x16x32_bf16 v[92:95], v[8:11], v[64:67], v[92:95]
	v_mfma_f32_16x16x32_bf16 v[96:99], v[16:19], v[64:67], v[96:99]
	s_setprio 0
	s_setprio 1
	v_mfma_f32_16x16x32_bf16 v[100:103], v[20:23], v[36:39], 0
	v_mfma_f32_16x16x32_bf16 v[36:39], v[28:31], v[36:39], 0
	v_mfma_f32_16x16x32_bf16 v[100:103], v[24:27], v[40:43], v[100:103]
	v_mfma_f32_16x16x32_bf16 v[40:43], v[32:35], v[40:43], v[36:39]
	v_mfma_f32_16x16x32_bf16 v[36:39], v[20:23], v[44:47], 0
	v_mfma_f32_16x16x32_bf16 v[104:107], v[24:27], v[48:51], v[36:39]
	v_mfma_f32_16x16x32_bf16 v[36:39], v[28:31], v[44:47], 0
	v_mfma_f32_16x16x32_bf16 v[48:51], v[32:35], v[48:51], v[36:39]
	v_mfma_f32_16x16x32_bf16 v[36:39], v[20:23], v[52:55], 0
	v_mfma_f32_16x16x32_bf16 v[108:111], v[24:27], v[56:59], v[36:39]
	v_mfma_f32_16x16x32_bf16 v[36:39], v[28:31], v[52:55], 0
	v_mfma_f32_16x16x32_bf16 v[56:59], v[32:35], v[56:59], v[36:39]
	v_mfma_f32_16x16x32_bf16 v[36:39], v[20:23], v[60:63], 0
	v_mfma_f32_16x16x32_bf16 v[112:115], v[24:27], v[64:67], v[36:39]
	v_mfma_f32_16x16x32_bf16 v[36:39], v[28:31], v[60:63], 0
	v_mfma_f32_16x16x32_bf16 v[64:67], v[32:35], v[64:67], v[36:39]
	s_setprio 0
	s_barrier
	s_add_i32 s82, s82, s6
	s_mov_b64 s[8:9], s[30:31]
	s_mov_b32 m0, s82
	s_add_i32 s83, s82, 0x2000
	s_nop 0
	ds_read_b128 v[36:39], v246 offset:16384
	ds_read_b128 v[44:47], v246 offset:17408
	ds_read_b128 v[52:55], v246 offset:18432
	ds_read_b128 v[60:63], v246 offset:19456
	ds_read_b128 v[116:119], v246 offset:20480
	ds_read_b128 v[120:123], v246 offset:21504
	ds_read_b128 v[124:127], v246 offset:22528
	ds_read_b128 v[128:131], v246 offset:23552
	s_nop 0
	global_load_lds_dwordx4 v248, s[8:9]
	s_mov_b32 m0, s83
	s_nop 0
	global_load_lds_dwordx4 v247, s[8:9]
	s_add_u32 s8, s30, s46
	s_addc_u32 s9, s31, s47
	s_add_i32 s30, s84, s6
	s_mov_b32 m0, s30
	s_add_i32 s31, s30, 0x2000
	s_nop 0
	global_load_lds_dwordx4 v248, s[8:9]
	s_mov_b32 m0, s31
	s_nop 0
	global_load_lds_dwordx4 v247, s[8:9]
	s_waitcnt vmcnt(6)
	s_waitcnt lgkmcnt(0)
	s_barrier
	s_setprio 1
	s_waitcnt lgkmcnt(0)
	v_mfma_f32_16x16x32_bf16 v[134:137], v[4:7], v[36:39], 0
	v_mfma_f32_16x16x32_bf16 v[144:147], v[4:7], v[52:55], 0
	v_mfma_f32_16x16x32_bf16 v[152:155], v[4:7], v[116:119], 0
	v_mfma_f32_16x16x32_bf16 v[4:7], v[4:7], v[124:127], 0
	v_mfma_f32_16x16x32_bf16 v[140:143], v[12:15], v[36:39], 0
	v_mfma_f32_16x16x32_bf16 v[148:151], v[12:15], v[52:55], 0
	v_mfma_f32_16x16x32_bf16 v[156:159], v[12:15], v[116:119], 0
	v_mfma_f32_16x16x32_bf16 v[160:163], v[8:11], v[128:131], v[4:7]
	v_mfma_f32_16x16x32_bf16 v[4:7], v[12:15], v[124:127], 0
	v_mfma_f32_16x16x32_bf16 v[136:139], v[8:11], v[44:47], v[134:137]
	v_mfma_f32_16x16x32_bf16 v[140:143], v[16:19], v[44:47], v[140:143]
	v_mfma_f32_16x16x32_bf16 v[144:147], v[8:11], v[60:63], v[144:147]
	v_mfma_f32_16x16x32_bf16 v[148:151], v[16:19], v[60:63], v[148:151]
	v_mfma_f32_16x16x32_bf16 v[152:155], v[8:11], v[120:123], v[152:155]
	v_mfma_f32_16x16x32_bf16 v[156:159], v[16:19], v[120:123], v[156:159]
	v_mfma_f32_16x16x32_bf16 v[164:167], v[16:19], v[128:131], v[4:7]
	s_setprio 0
	s_setprio 1
	v_mfma_f32_16x16x32_bf16 v[4:7], v[20:23], v[36:39], 0
	v_mfma_f32_16x16x32_bf16 v[168:171], v[24:27], v[44:47], v[4:7]
	v_mfma_f32_16x16x32_bf16 v[4:7], v[28:31], v[36:39], 0
	v_mfma_f32_16x16x32_bf16 v[172:175], v[32:35], v[44:47], v[4:7]
	v_mfma_f32_16x16x32_bf16 v[4:7], v[20:23], v[52:55], 0
	v_mfma_f32_16x16x32_bf16 v[176:179], v[24:27], v[60:63], v[4:7]
	v_mfma_f32_16x16x32_bf16 v[4:7], v[28:31], v[52:55], 0
	v_mfma_f32_16x16x32_bf16 v[180:183], v[32:35], v[60:63], v[4:7]
	v_mfma_f32_16x16x32_bf16 v[4:7], v[20:23], v[116:119], 0
	v_mfma_f32_16x16x32_bf16 v[184:187], v[24:27], v[120:123], v[4:7]
	v_mfma_f32_16x16x32_bf16 v[4:7], v[28:31], v[116:119], 0
	v_mfma_f32_16x16x32_bf16 v[120:123], v[32:35], v[120:123], v[4:7]
	v_mfma_f32_16x16x32_bf16 v[4:7], v[20:23], v[124:127], 0
	v_mfma_f32_16x16x32_bf16 v[188:191], v[24:27], v[128:131], v[4:7]
	v_mfma_f32_16x16x32_bf16 v[4:7], v[28:31], v[124:127], 0
	v_mfma_f32_16x16x32_bf16 v[128:131], v[32:35], v[128:131], v[4:7]
	s_setprio 0
	s_barrier
	s_add_i32 s84, 0, 0x18000
	s_add_i32 s16, 0, 0x1c000
	v_add_u32_e32 v134, s84, v245
	v_add_u32_e32 v135, s16, v245
	ds_read_b128 v[116:119], v134
	ds_read_b128 v[124:127], v134 offset:1024
	ds_read_b128 v[192:195], v134 offset:2048
	ds_read_b128 v[196:199], v134 offset:3072
	ds_read_b128 v[200:203], v135
	ds_read_b128 v[204:207], v135 offset:1024
	ds_read_b128 v[216:219], v135 offset:2048
	ds_read_b128 v[220:223], v135 offset:3072
	s_mov_b32 m0, s7
	s_mov_b64 s[8:9], s[18:19]
	ds_read_b128 v[44:47], v246 offset:32768
	ds_read_b128 v[52:55], v246 offset:33792
	ds_read_b128 v[60:63], v246 offset:34816
	ds_read_b128 v[224:227], v246 offset:35840
	ds_read_b128 v[228:231], v246 offset:36864
	ds_read_b128 v[232:235], v246 offset:37888
	ds_read_b128 v[236:239], v246 offset:38912
	ds_read_b128 v[250:253], v246 offset:39936
	s_nop 0
	global_load_lds_dwordx4 v242, s[8:9]
	s_mov_b32 m0, s58
	s_nop 0
	global_load_lds_dwordx4 v2, s[8:9]
	s_add_u32 s8, s18, s46
	s_addc_u32 s9, s19, s47
	s_mov_b32 m0, s59
	s_nop 0
	global_load_lds_dwordx4 v242, s[8:9]
	s_mov_b32 m0, s69
	s_nop 0
	global_load_lds_dwordx4 v2, s[8:9]
	s_waitcnt vmcnt(8)
	s_waitcnt lgkmcnt(0)
	s_barrier
	s_setprio 1
	s_waitcnt lgkmcnt(0)
	v_mfma_f32_16x16x32_bf16 v[4:7], v[116:119], v[44:47], v[68:71]
	v_mfma_f32_16x16x32_bf16 v[4:7], v[124:127], v[52:55], v[4:7]
	v_mfma_f32_16x16x32_bf16 v[8:11], v[192:195], v[44:47], v[72:75]
	v_mfma_f32_16x16x32_bf16 v[8:11], v[196:199], v[52:55], v[8:11]
	v_mfma_f32_16x16x32_bf16 v[12:15], v[116:119], v[60:63], v[76:79]
	v_mfma_f32_16x16x32_bf16 v[12:15], v[124:127], v[224:227], v[12:15]
	v_mfma_f32_16x16x32_bf16 v[16:19], v[192:195], v[60:63], v[80:83]
	v_mfma_f32_16x16x32_bf16 v[16:19], v[196:199], v[224:227], v[16:19]
	v_mfma_f32_16x16x32_bf16 v[20:23], v[116:119], v[228:231], v[84:87]
	v_mfma_f32_16x16x32_bf16 v[20:23], v[124:127], v[232:235], v[20:23]
	v_mfma_f32_16x16x32_bf16 v[24:27], v[192:195], v[228:231], v[88:91]
	v_mfma_f32_16x16x32_bf16 v[24:27], v[196:199], v[232:235], v[24:27]
	v_mfma_f32_16x16x32_bf16 v[28:31], v[116:119], v[236:239], v[92:95]
	v_mfma_f32_16x16x32_bf16 v[28:31], v[124:127], v[250:253], v[28:31]
	v_mfma_f32_16x16x32_bf16 v[32:35], v[192:195], v[236:239], v[96:99]
	v_mfma_f32_16x16x32_bf16 v[32:35], v[196:199], v[250:253], v[32:35]
	s_setprio 0
	s_setprio 1
	v_mfma_f32_16x16x32_bf16 v[36:39], v[200:203], v[44:47], v[100:103]
	v_mfma_f32_16x16x32_bf16 v[40:43], v[216:219], v[44:47], v[40:43]
	v_mfma_f32_16x16x32_bf16 v[36:39], v[204:207], v[52:55], v[36:39]
	v_mfma_f32_16x16x32_bf16 v[40:43], v[220:223], v[52:55], v[40:43]
	v_mfma_f32_16x16x32_bf16 v[44:47], v[200:203], v[60:63], v[104:107]
	v_mfma_f32_16x16x32_bf16 v[48:51], v[216:219], v[60:63], v[48:51]
	v_mfma_f32_16x16x32_bf16 v[52:55], v[200:203], v[228:231], v[108:111]
	v_mfma_f32_16x16x32_bf16 v[56:59], v[216:219], v[228:231], v[56:59]
	v_mfma_f32_16x16x32_bf16 v[60:63], v[200:203], v[236:239], v[112:115]
	v_mfma_f32_16x16x32_bf16 v[64:67], v[216:219], v[236:239], v[64:67]
	v_mfma_f32_16x16x32_bf16 v[44:47], v[204:207], v[224:227], v[44:47]
	v_mfma_f32_16x16x32_bf16 v[48:51], v[220:223], v[224:227], v[48:51]
	v_mfma_f32_16x16x32_bf16 v[52:55], v[204:207], v[232:235], v[52:55]
	v_mfma_f32_16x16x32_bf16 v[56:59], v[220:223], v[232:235], v[56:59]
	v_mfma_f32_16x16x32_bf16 v[60:63], v[204:207], v[250:253], v[60:63]
	v_mfma_f32_16x16x32_bf16 v[64:67], v[220:223], v[250:253], v[64:67]
	s_setprio 0
	s_barrier
	s_add_i32 s84, s84, s6
	s_mov_b64 s[8:9], s[28:29]
	s_mov_b32 m0, s84
	s_add_i32 s85, s84, 0x2000
	ds_read_b128 v[104:107], v246 offset:49152
	ds_read_b128 v[108:111], v246 offset:50176
	ds_read_b128 v[112:115], v246 offset:51200
	ds_read_b128 v[224:227], v246 offset:52224
	ds_read_b128 v[228:231], v246 offset:53248
	ds_read_b128 v[232:235], v246 offset:54272
	ds_read_b128 v[236:239], v246 offset:55296
	ds_read_b128 v[250:253], v246 offset:56320
	s_nop 0
	global_load_lds_dwordx4 v248, s[8:9]
	s_mov_b32 m0, s85
	s_nop 0
	global_load_lds_dwordx4 v247, s[8:9]
	s_add_u32 s8, s28, s46
	s_addc_u32 s9, s29, s47
	s_add_i32 s28, s16, s6
	s_mov_b32 m0, s28
	s_add_i32 s29, s28, 0x2000
	s_nop 0
	global_load_lds_dwordx4 v248, s[8:9]
	s_mov_b32 m0, s29
	s_nop 0
	global_load_lds_dwordx4 v247, s[8:9]
	s_waitcnt vmcnt(6)
	s_waitcnt lgkmcnt(0)
	s_barrier
	s_setprio 1
	s_waitcnt lgkmcnt(0)
	v_mfma_f32_16x16x32_bf16 v[68:71], v[116:119], v[104:107], v[136:139]
	v_mfma_f32_16x16x32_bf16 v[68:71], v[124:127], v[108:111], v[68:71]
	v_mfma_f32_16x16x32_bf16 v[72:75], v[192:195], v[104:107], v[140:143]
	v_mfma_f32_16x16x32_bf16 v[72:75], v[196:199], v[108:111], v[72:75]
	v_mfma_f32_16x16x32_bf16 v[76:79], v[116:119], v[112:115], v[144:147]
	v_mfma_f32_16x16x32_bf16 v[76:79], v[124:127], v[224:227], v[76:79]
	v_mfma_f32_16x16x32_bf16 v[80:83], v[192:195], v[112:115], v[148:151]
	v_mfma_f32_16x16x32_bf16 v[80:83], v[196:199], v[224:227], v[80:83]
	v_mfma_f32_16x16x32_bf16 v[84:87], v[116:119], v[228:231], v[152:155]
	v_mfma_f32_16x16x32_bf16 v[84:87], v[124:127], v[232:235], v[84:87]
	v_mfma_f32_16x16x32_bf16 v[88:91], v[192:195], v[228:231], v[156:159]
	v_mfma_f32_16x16x32_bf16 v[88:91], v[196:199], v[232:235], v[88:91]
	v_mfma_f32_16x16x32_bf16 v[92:95], v[116:119], v[236:239], v[160:163]
	v_mfma_f32_16x16x32_bf16 v[92:95], v[124:127], v[250:253], v[92:95]
	v_mfma_f32_16x16x32_bf16 v[96:99], v[192:195], v[236:239], v[164:167]
	v_mfma_f32_16x16x32_bf16 v[96:99], v[196:199], v[250:253], v[96:99]
	s_setprio 0
	s_setprio 1
	v_mfma_f32_16x16x32_bf16 v[100:103], v[200:203], v[104:107], v[168:171]
	v_mfma_f32_16x16x32_bf16 v[104:107], v[216:219], v[104:107], v[172:175]
	v_mfma_f32_16x16x32_bf16 v[100:103], v[204:207], v[108:111], v[100:103]
	v_mfma_f32_16x16x32_bf16 v[104:107], v[220:223], v[108:111], v[104:107]
	v_mfma_f32_16x16x32_bf16 v[108:111], v[200:203], v[112:115], v[176:179]
	v_mfma_f32_16x16x32_bf16 v[112:115], v[216:219], v[112:115], v[180:183]
	v_mfma_f32_16x16x32_bf16 v[116:119], v[200:203], v[228:231], v[184:187]
	v_mfma_f32_16x16x32_bf16 v[120:123], v[216:219], v[228:231], v[120:123]
	v_mfma_f32_16x16x32_bf16 v[124:127], v[200:203], v[236:239], v[188:191]
	v_mfma_f32_16x16x32_bf16 v[128:131], v[216:219], v[236:239], v[128:131]
	v_mfma_f32_16x16x32_bf16 v[108:111], v[204:207], v[224:227], v[108:111]
	v_mfma_f32_16x16x32_bf16 v[112:115], v[220:223], v[224:227], v[112:115]
	v_mfma_f32_16x16x32_bf16 v[116:119], v[204:207], v[232:235], v[116:119]
	v_mfma_f32_16x16x32_bf16 v[120:123], v[220:223], v[232:235], v[120:123]
	v_mfma_f32_16x16x32_bf16 v[124:127], v[204:207], v[250:253], v[124:127]
	v_mfma_f32_16x16x32_bf16 v[128:131], v[220:223], v[250:253], v[128:131]
	s_setprio 0
	s_barrier
	s_andn2_b64 vcc, exec, s[56:57]
	s_cbranch_vccnz .LBB0_881
	s_add_u32 s86, s20, 0x200
	s_addc_u32 s87, s21, 0
	s_add_u32 s26, s26, 0x200
	s_addc_u32 s27, s27, 0
	s_mov_b32 s88, 4
	.p2align	6
	s_nop 0
	s_nop 0
	s_nop 0
	s_nop 0
	s_nop 0
	s_nop 0
	s_nop 0
	s_nop 0
	s_nop 0
	s_nop 0
	s_nop 0
	s_nop 0

.LBB0_1019:
	s_add_u32 s18, s72, 0x100
	s_addc_u32 s19, s73, 0
	s_add_u32 s16, s66, 0x100
	s_addc_u32 s17, s67, 0
	s_and_b64 s[8:9], s[30:31], exec
	s_cselect_b32 s17, s43, s17
	s_cselect_b32 s16, s42, s16
	s_add_i32 s89, 0, 0x10000
	s_and_b64 s[8:9], s[30:31], exec
	s_cselect_b32 s69, s65, s19
	s_cselect_b32 s68, s64, s18
	s_add_i32 s91, 0, 0x14000
	v_add_u32_e32 v132, s89, v140
	v_add_u32_e32 v133, s91, v140
	ds_read_b128 v[4:7], v132
	ds_read_b128 v[8:11], v132 offset:1024
	ds_read_b128 v[12:15], v132 offset:2048
	ds_read_b128 v[16:19], v132 offset:3072
	ds_read_b128 v[20:23], v133
	ds_read_b128 v[24:27], v133 offset:1024
	ds_read_b128 v[28:31], v133 offset:2048
	ds_read_b128 v[32:35], v133 offset:3072
	s_add_u32 s8, s72, 0x80
	s_addc_u32 s9, s73, 0
	s_add_i32 s85, s78, 0x8000
	s_add_i32 s86, s78, 0xa000
	s_mov_b64 s[18:19], s[8:9]
	s_mov_b32 m0, s85
	s_add_u32 s8, s8, s20
	ds_read_b128 v[36:39], v141 offset:8192
	ds_read_b128 v[40:43], v141 offset:9216
	ds_read_b128 v[44:47], v141 offset:10240
	ds_read_b128 v[48:51], v141 offset:11264
	ds_read_b128 v[52:55], v141 offset:12288
	ds_read_b128 v[56:59], v141 offset:13312
	ds_read_b128 v[60:63], v141 offset:14336
	ds_read_b128 v[64:67], v141 offset:15360
	s_addc_u32 s9, s9, s21
	global_load_lds_dwordx4 v137, s[18:19]
	s_mov_b32 m0, s86
	s_add_i32 s87, s78, 0xc000
	global_load_lds_dwordx4 v136, s[18:19]
	s_mov_b32 m0, s87
	s_add_i32 s88, s78, 0xe000
	s_add_u32 s18, s16, 0x80
	global_load_lds_dwordx4 v137, s[8:9]
	s_mov_b32 m0, s88
	s_addc_u32 s19, s17, 0
	global_load_lds_dwordx4 v136, s[8:9]
	s_waitcnt vmcnt(8)
	s_waitcnt lgkmcnt(0)
	s_barrier
	s_setprio 1
	s_waitcnt lgkmcnt(0)
	v_mfma_f32_16x16x32_bf16 v[68:71], v[4:7], v[36:39], 0
	v_mfma_f32_16x16x32_bf16 v[72:75], v[12:15], v[36:39], 0
	v_mfma_f32_16x16x32_bf16 v[76:79], v[4:7], v[44:47], 0
	v_mfma_f32_16x16x32_bf16 v[80:83], v[12:15], v[44:47], 0
	v_mfma_f32_16x16x32_bf16 v[84:87], v[4:7], v[52:55], 0
	v_mfma_f32_16x16x32_bf16 v[88:91], v[12:15], v[52:55], 0
	v_mfma_f32_16x16x32_bf16 v[92:95], v[4:7], v[60:63], 0
	v_mfma_f32_16x16x32_bf16 v[96:99], v[12:15], v[60:63], 0
	v_mfma_f32_16x16x32_bf16 v[68:71], v[8:11], v[40:43], v[68:71]
	v_mfma_f32_16x16x32_bf16 v[72:75], v[16:19], v[40:43], v[72:75]
	v_mfma_f32_16x16x32_bf16 v[76:79], v[8:11], v[48:51], v[76:79]
	v_mfma_f32_16x16x32_bf16 v[80:83], v[16:19], v[48:51], v[80:83]
	v_mfma_f32_16x16x32_bf16 v[84:87], v[8:11], v[56:59], v[84:87]
	v_mfma_f32_16x16x32_bf16 v[88:91], v[16:19], v[56:59], v[88:91]
	v_mfma_f32_16x16x32_bf16 v[92:95], v[8:11], v[64:67], v[92:95]
	v_mfma_f32_16x16x32_bf16 v[96:99], v[16:19], v[64:67], v[96:99]
	s_setprio 0
	s_setprio 1
	v_mfma_f32_16x16x32_bf16 v[100:103], v[20:23], v[36:39], 0
	v_mfma_f32_16x16x32_bf16 v[36:39], v[28:31], v[36:39], 0
	v_mfma_f32_16x16x32_bf16 v[100:103], v[24:27], v[40:43], v[100:103]
	v_mfma_f32_16x16x32_bf16 v[40:43], v[32:35], v[40:43], v[36:39]
	v_mfma_f32_16x16x32_bf16 v[36:39], v[20:23], v[44:47], 0
	v_mfma_f32_16x16x32_bf16 v[104:107], v[24:27], v[48:51], v[36:39]
	v_mfma_f32_16x16x32_bf16 v[36:39], v[28:31], v[44:47], 0
	v_mfma_f32_16x16x32_bf16 v[48:51], v[32:35], v[48:51], v[36:39]
	v_mfma_f32_16x16x32_bf16 v[36:39], v[20:23], v[52:55], 0
	v_mfma_f32_16x16x32_bf16 v[108:111], v[24:27], v[56:59], v[36:39]
	v_mfma_f32_16x16x32_bf16 v[36:39], v[28:31], v[52:55], 0
	v_mfma_f32_16x16x32_bf16 v[56:59], v[32:35], v[56:59], v[36:39]
	v_mfma_f32_16x16x32_bf16 v[36:39], v[20:23], v[60:63], 0
	v_mfma_f32_16x16x32_bf16 v[112:115], v[24:27], v[64:67], v[36:39]
	v_mfma_f32_16x16x32_bf16 v[36:39], v[28:31], v[60:63], 0
	v_mfma_f32_16x16x32_bf16 v[64:67], v[32:35], v[64:67], v[36:39]
	s_setprio 0
	s_barrier
	s_add_i32 s89, s89, s77
	s_mov_b64 s[8:9], s[16:17]
	s_mov_b32 m0, s89
	s_add_i32 s90, s89, 0x2000
	s_nop 0
	ds_read_b128 v[36:39], v141 offset:24576
	ds_read_b128 v[44:47], v141 offset:25600
	ds_read_b128 v[52:55], v141 offset:26624
	ds_read_b128 v[60:63], v141 offset:27648
	ds_read_b128 v[116:119], v141 offset:28672
	ds_read_b128 v[120:123], v141 offset:29696
	ds_read_b128 v[124:127], v141 offset:30720
	ds_read_b128 v[128:131], v141 offset:31744
	s_nop 0
	global_load_lds_dwordx4 v143, s[8:9]
	s_mov_b32 m0, s90
	s_nop 0
	global_load_lds_dwordx4 v142, s[8:9]
	s_add_u32 s8, s16, s20
	s_addc_u32 s9, s17, s21
	s_add_i32 s91, s91, s77
	s_mov_b32 m0, s91
	s_add_i32 s92, s91, 0x2000
	s_nop 0
	global_load_lds_dwordx4 v143, s[8:9]
	s_mov_b32 m0, s92
	s_nop 0
	global_load_lds_dwordx4 v142, s[8:9]
	s_waitcnt vmcnt(6)
	s_waitcnt lgkmcnt(0)
	s_barrier
	s_setprio 1
	s_waitcnt lgkmcnt(0)
	v_mfma_f32_16x16x32_bf16 v[144:147], v[4:7], v[36:39], 0
	v_mfma_f32_16x16x32_bf16 v[152:155], v[4:7], v[52:55], 0
	v_mfma_f32_16x16x32_bf16 v[160:163], v[4:7], v[116:119], 0
	v_mfma_f32_16x16x32_bf16 v[4:7], v[4:7], v[124:127], 0
	v_mfma_f32_16x16x32_bf16 v[148:151], v[12:15], v[36:39], 0
	v_mfma_f32_16x16x32_bf16 v[156:159], v[12:15], v[52:55], 0
	v_mfma_f32_16x16x32_bf16 v[164:167], v[12:15], v[116:119], 0
	v_mfma_f32_16x16x32_bf16 v[168:171], v[8:11], v[128:131], v[4:7]
	v_mfma_f32_16x16x32_bf16 v[4:7], v[12:15], v[124:127], 0
	v_mfma_f32_16x16x32_bf16 v[144:147], v[8:11], v[44:47], v[144:147]
	v_mfma_f32_16x16x32_bf16 v[148:151], v[16:19], v[44:47], v[148:151]
	v_mfma_f32_16x16x32_bf16 v[152:155], v[8:11], v[60:63], v[152:155]
	v_mfma_f32_16x16x32_bf16 v[156:159], v[16:19], v[60:63], v[156:159]
	v_mfma_f32_16x16x32_bf16 v[160:163], v[8:11], v[120:123], v[160:163]
	v_mfma_f32_16x16x32_bf16 v[164:167], v[16:19], v[120:123], v[164:167]
	v_mfma_f32_16x16x32_bf16 v[172:175], v[16:19], v[128:131], v[4:7]
	s_setprio 0
	s_setprio 1
	v_mfma_f32_16x16x32_bf16 v[4:7], v[20:23], v[36:39], 0
	v_mfma_f32_16x16x32_bf16 v[176:179], v[24:27], v[44:47], v[4:7]
	v_mfma_f32_16x16x32_bf16 v[4:7], v[28:31], v[36:39], 0
	v_mfma_f32_16x16x32_bf16 v[180:183], v[32:35], v[44:47], v[4:7]
	v_mfma_f32_16x16x32_bf16 v[4:7], v[20:23], v[52:55], 0
	v_mfma_f32_16x16x32_bf16 v[184:187], v[24:27], v[60:63], v[4:7]
	v_mfma_f32_16x16x32_bf16 v[4:7], v[28:31], v[52:55], 0
	v_mfma_f32_16x16x32_bf16 v[188:191], v[32:35], v[60:63], v[4:7]
	v_mfma_f32_16x16x32_bf16 v[4:7], v[20:23], v[116:119], 0
	v_mfma_f32_16x16x32_bf16 v[192:195], v[24:27], v[120:123], v[4:7]
	v_mfma_f32_16x16x32_bf16 v[4:7], v[28:31], v[116:119], 0
	v_mfma_f32_16x16x32_bf16 v[120:123], v[32:35], v[120:123], v[4:7]
	v_mfma_f32_16x16x32_bf16 v[4:7], v[20:23], v[124:127], 0
	v_mfma_f32_16x16x32_bf16 v[196:199], v[24:27], v[128:131], v[4:7]
	v_mfma_f32_16x16x32_bf16 v[4:7], v[28:31], v[124:127], 0
	v_mfma_f32_16x16x32_bf16 v[128:131], v[32:35], v[128:131], v[4:7]
	s_setprio 0
	s_barrier
	s_add_i32 s16, 0, 0x18000
	s_add_i32 s93, 0, 0x1c000
	v_add_u32_e32 v134, s16, v140
	v_add_u32_e32 v135, s93, v140
	ds_read_b128 v[116:119], v134
	ds_read_b128 v[124:127], v134 offset:1024
	ds_read_b128 v[200:203], v134 offset:2048
	ds_read_b128 v[204:207], v134 offset:3072
	ds_read_b128 v[216:219], v135
	ds_read_b128 v[220:223], v135 offset:1024
	ds_read_b128 v[224:227], v135 offset:2048
	ds_read_b128 v[228:231], v135 offset:3072
	s_mov_b32 m0, s78
	s_mov_b64 s[8:9], s[68:69]
	ds_read_b128 v[44:47], v141 offset:40960
	ds_read_b128 v[52:55], v141 offset:41984
	ds_read_b128 v[60:63], v141 offset:43008
	ds_read_b128 v[232:235], v141 offset:44032
	ds_read_b128 v[236:239], v141 offset:45056
	ds_read_b128 v[242:245], v141 offset:46080
	ds_read_b128 v[246:249], v141 offset:47104
	ds_read_b128 v[250:253], v141 offset:48128
	s_nop 0
	global_load_lds_dwordx4 v137, s[8:9]
	s_mov_b32 m0, s79
	s_nop 0
	global_load_lds_dwordx4 v136, s[8:9]
	s_add_u32 s8, s68, s20
	s_addc_u32 s9, s69, s21
	s_mov_b32 m0, s80
	s_nop 0
	global_load_lds_dwordx4 v137, s[8:9]
	s_mov_b32 m0, s81
	s_nop 0
	global_load_lds_dwordx4 v136, s[8:9]
	s_waitcnt vmcnt(8)
	s_waitcnt lgkmcnt(0)
	s_barrier
	s_setprio 1
	s_waitcnt lgkmcnt(0)
	v_mfma_f32_16x16x32_bf16 v[4:7], v[116:119], v[44:47], v[68:71]
	v_mfma_f32_16x16x32_bf16 v[4:7], v[124:127], v[52:55], v[4:7]
	v_mfma_f32_16x16x32_bf16 v[8:11], v[200:203], v[44:47], v[72:75]
	v_mfma_f32_16x16x32_bf16 v[8:11], v[204:207], v[52:55], v[8:11]
	v_mfma_f32_16x16x32_bf16 v[12:15], v[116:119], v[60:63], v[76:79]
	v_mfma_f32_16x16x32_bf16 v[12:15], v[124:127], v[232:235], v[12:15]
	v_mfma_f32_16x16x32_bf16 v[16:19], v[200:203], v[60:63], v[80:83]
	v_mfma_f32_16x16x32_bf16 v[16:19], v[204:207], v[232:235], v[16:19]
	v_mfma_f32_16x16x32_bf16 v[20:23], v[116:119], v[236:239], v[84:87]
	v_mfma_f32_16x16x32_bf16 v[20:23], v[124:127], v[242:245], v[20:23]
	v_mfma_f32_16x16x32_bf16 v[24:27], v[200:203], v[236:239], v[88:91]
	v_mfma_f32_16x16x32_bf16 v[24:27], v[204:207], v[242:245], v[24:27]
	v_mfma_f32_16x16x32_bf16 v[28:31], v[116:119], v[246:249], v[92:95]
	v_mfma_f32_16x16x32_bf16 v[28:31], v[124:127], v[250:253], v[28:31]
	v_mfma_f32_16x16x32_bf16 v[32:35], v[200:203], v[246:249], v[96:99]
	v_mfma_f32_16x16x32_bf16 v[32:35], v[204:207], v[250:253], v[32:35]
	s_setprio 0
	s_setprio 1
	v_mfma_f32_16x16x32_bf16 v[36:39], v[216:219], v[44:47], v[100:103]
	v_mfma_f32_16x16x32_bf16 v[40:43], v[224:227], v[44:47], v[40:43]
	v_mfma_f32_16x16x32_bf16 v[36:39], v[220:223], v[52:55], v[36:39]
	v_mfma_f32_16x16x32_bf16 v[40:43], v[228:231], v[52:55], v[40:43]
	v_mfma_f32_16x16x32_bf16 v[44:47], v[216:219], v[60:63], v[104:107]
	v_mfma_f32_16x16x32_bf16 v[48:51], v[224:227], v[60:63], v[48:51]
	v_mfma_f32_16x16x32_bf16 v[52:55], v[216:219], v[236:239], v[108:111]
	v_mfma_f32_16x16x32_bf16 v[56:59], v[224:227], v[236:239], v[56:59]
	v_mfma_f32_16x16x32_bf16 v[60:63], v[216:219], v[246:249], v[112:115]
	v_mfma_f32_16x16x32_bf16 v[64:67], v[224:227], v[246:249], v[64:67]
	v_mfma_f32_16x16x32_bf16 v[44:47], v[220:223], v[232:235], v[44:47]
	v_mfma_f32_16x16x32_bf16 v[48:51], v[228:231], v[232:235], v[48:51]
	v_mfma_f32_16x16x32_bf16 v[52:55], v[220:223], v[242:245], v[52:55]
	v_mfma_f32_16x16x32_bf16 v[56:59], v[228:231], v[242:245], v[56:59]
	v_mfma_f32_16x16x32_bf16 v[60:63], v[220:223], v[250:253], v[60:63]
	v_mfma_f32_16x16x32_bf16 v[64:67], v[228:231], v[250:253], v[64:67]
	s_setprio 0
	s_barrier
	s_add_i32 s68, s16, s77
	s_mov_b64 s[8:9], s[18:19]
	s_mov_b32 m0, s68
	s_add_i32 s69, s68, 0x2000
	ds_read_b128 v[104:107], v141 offset:57344
	ds_read_b128 v[108:111], v141 offset:58368
	ds_read_b128 v[112:115], v141 offset:59392
	ds_read_b128 v[232:235], v141 offset:60416
	ds_read_b128 v[236:239], v141 offset:61440
	ds_read_b128 v[242:245], v141 offset:62464
	ds_read_b128 v[246:249], v141 offset:63488
	ds_read_b128 v[250:253], v141 offset:64512
	s_nop 0
	global_load_lds_dwordx4 v143, s[8:9]
	s_mov_b32 m0, s69
	s_nop 0
	global_load_lds_dwordx4 v142, s[8:9]
	s_add_u32 s8, s18, s20
	s_addc_u32 s9, s19, s21
	s_add_i32 s93, s93, s77
	s_mov_b32 m0, s93
	s_add_i32 s94, s93, 0x2000
	s_nop 0
	global_load_lds_dwordx4 v143, s[8:9]
	s_mov_b32 m0, s94
	s_nop 0
	global_load_lds_dwordx4 v142, s[8:9]
	s_waitcnt vmcnt(6)
	s_waitcnt lgkmcnt(0)
	s_barrier
	s_setprio 1
	s_waitcnt lgkmcnt(0)
	v_mfma_f32_16x16x32_bf16 v[68:71], v[116:119], v[104:107], v[144:147]
	v_mfma_f32_16x16x32_bf16 v[68:71], v[124:127], v[108:111], v[68:71]
	v_mfma_f32_16x16x32_bf16 v[72:75], v[200:203], v[104:107], v[148:151]
	v_mfma_f32_16x16x32_bf16 v[72:75], v[204:207], v[108:111], v[72:75]
	v_mfma_f32_16x16x32_bf16 v[76:79], v[116:119], v[112:115], v[152:155]
	v_mfma_f32_16x16x32_bf16 v[76:79], v[124:127], v[232:235], v[76:79]
	v_mfma_f32_16x16x32_bf16 v[80:83], v[200:203], v[112:115], v[156:159]
	v_mfma_f32_16x16x32_bf16 v[80:83], v[204:207], v[232:235], v[80:83]
	v_mfma_f32_16x16x32_bf16 v[84:87], v[116:119], v[236:239], v[160:163]
	v_mfma_f32_16x16x32_bf16 v[84:87], v[124:127], v[242:245], v[84:87]
	v_mfma_f32_16x16x32_bf16 v[88:91], v[200:203], v[236:239], v[164:167]
	v_mfma_f32_16x16x32_bf16 v[88:91], v[204:207], v[242:245], v[88:91]
	v_mfma_f32_16x16x32_bf16 v[92:95], v[116:119], v[246:249], v[168:171]
	v_mfma_f32_16x16x32_bf16 v[92:95], v[124:127], v[250:253], v[92:95]
	v_mfma_f32_16x16x32_bf16 v[96:99], v[200:203], v[246:249], v[172:175]
	v_mfma_f32_16x16x32_bf16 v[96:99], v[204:207], v[250:253], v[96:99]
	s_setprio 0
	s_setprio 1
	v_mfma_f32_16x16x32_bf16 v[100:103], v[216:219], v[104:107], v[176:179]
	v_mfma_f32_16x16x32_bf16 v[104:107], v[224:227], v[104:107], v[180:183]
	v_mfma_f32_16x16x32_bf16 v[100:103], v[220:223], v[108:111], v[100:103]
	v_mfma_f32_16x16x32_bf16 v[104:107], v[228:231], v[108:111], v[104:107]
	v_mfma_f32_16x16x32_bf16 v[108:111], v[216:219], v[112:115], v[184:187]
	v_mfma_f32_16x16x32_bf16 v[112:115], v[224:227], v[112:115], v[188:191]
	v_mfma_f32_16x16x32_bf16 v[116:119], v[216:219], v[236:239], v[192:195]
	v_mfma_f32_16x16x32_bf16 v[120:123], v[224:227], v[236:239], v[120:123]
	v_mfma_f32_16x16x32_bf16 v[124:127], v[216:219], v[246:249], v[196:199]
	v_mfma_f32_16x16x32_bf16 v[128:131], v[224:227], v[246:249], v[128:131]
	v_mfma_f32_16x16x32_bf16 v[108:111], v[220:223], v[232:235], v[108:111]
	v_mfma_f32_16x16x32_bf16 v[112:115], v[228:231], v[232:235], v[112:115]
	v_mfma_f32_16x16x32_bf16 v[116:119], v[220:223], v[242:245], v[116:119]
	v_mfma_f32_16x16x32_bf16 v[120:123], v[228:231], v[242:245], v[120:123]
	v_mfma_f32_16x16x32_bf16 v[124:127], v[220:223], v[250:253], v[124:127]
	v_mfma_f32_16x16x32_bf16 v[128:131], v[228:231], v[250:253], v[128:131]
	s_setprio 0
	s_barrier
	s_andn2_b64 vcc, exec, s[60:61]
	s_cbranch_vccnz .LBB0_1023
	s_add_u32 s95, s66, 0x200
	s_addc_u32 s96, s67, 0
	s_add_u32 s72, s72, 0x200
	s_addc_u32 s73, s73, 0
	s_mov_b32 s97, 4
	.p2align	6
	s_nop 0
	s_nop 0
	s_nop 0
	s_nop 0
	s_nop 0
	s_nop 0
	s_nop 0
	s_nop 0
	s_nop 0
	s_nop 0
	s_nop 0
	s_nop 0

.LBB0_1040:
	s_add_u32 s18, s66, 0x100
	s_addc_u32 s19, s67, 0
	s_add_u32 s16, s64, 0x100
	s_addc_u32 s17, s65, 0
	s_and_b64 s[8:9], s[30:31], exec
	s_cselect_b32 s17, s43, s17
	s_cselect_b32 s16, s42, s16
	s_add_i32 s87, 0, 0x10000
	s_and_b64 s[8:9], s[30:31], exec
	s_cselect_b32 s69, s41, s19
	s_cselect_b32 s68, s40, s18
	s_add_i32 s89, 0, 0x14000
	v_add_u32_e32 v132, s87, v140
	v_add_u32_e32 v133, s89, v140
	ds_read_b128 v[4:7], v132
	ds_read_b128 v[8:11], v132 offset:1024
	ds_read_b128 v[12:15], v132 offset:2048
	ds_read_b128 v[16:19], v132 offset:3072
	ds_read_b128 v[20:23], v133
	ds_read_b128 v[24:27], v133 offset:1024
	ds_read_b128 v[28:31], v133 offset:2048
	ds_read_b128 v[32:35], v133 offset:3072
	s_add_u32 s8, s66, 0x80
	s_addc_u32 s9, s67, 0
	s_add_i32 s83, s76, 0x8000
	s_add_i32 s84, s76, 0xa000
	s_mov_b64 s[18:19], s[8:9]
	s_mov_b32 m0, s83
	s_add_u32 s8, s8, s20
	ds_read_b128 v[36:39], v141
	ds_read_b128 v[40:43], v141 offset:1024
	ds_read_b128 v[44:47], v141 offset:2048
	ds_read_b128 v[48:51], v141 offset:3072
	ds_read_b128 v[52:55], v141 offset:4096
	ds_read_b128 v[56:59], v141 offset:5120
	ds_read_b128 v[60:63], v141 offset:6144
	ds_read_b128 v[64:67], v141 offset:7168
	s_addc_u32 s9, s9, s21
	global_load_lds_dwordx4 v137, s[18:19]
	s_mov_b32 m0, s84
	s_add_i32 s85, s76, 0xc000
	global_load_lds_dwordx4 v136, s[18:19]
	s_mov_b32 m0, s85
	s_add_i32 s86, s76, 0xe000
	s_add_u32 s18, s16, 0x80
	global_load_lds_dwordx4 v137, s[8:9]
	s_mov_b32 m0, s86
	s_addc_u32 s19, s17, 0
	global_load_lds_dwordx4 v136, s[8:9]
	s_waitcnt vmcnt(8)
	s_waitcnt lgkmcnt(0)
	s_barrier
	s_setprio 1
	s_waitcnt lgkmcnt(0)
	v_mfma_f32_16x16x32_bf16 v[68:71], v[4:7], v[36:39], 0
	v_mfma_f32_16x16x32_bf16 v[72:75], v[12:15], v[36:39], 0
	v_mfma_f32_16x16x32_bf16 v[76:79], v[4:7], v[44:47], 0
	v_mfma_f32_16x16x32_bf16 v[80:83], v[12:15], v[44:47], 0
	v_mfma_f32_16x16x32_bf16 v[84:87], v[4:7], v[52:55], 0
	v_mfma_f32_16x16x32_bf16 v[88:91], v[12:15], v[52:55], 0
	v_mfma_f32_16x16x32_bf16 v[92:95], v[4:7], v[60:63], 0
	v_mfma_f32_16x16x32_bf16 v[96:99], v[12:15], v[60:63], 0
	v_mfma_f32_16x16x32_bf16 v[68:71], v[8:11], v[40:43], v[68:71]
	v_mfma_f32_16x16x32_bf16 v[72:75], v[16:19], v[40:43], v[72:75]
	v_mfma_f32_16x16x32_bf16 v[76:79], v[8:11], v[48:51], v[76:79]
	v_mfma_f32_16x16x32_bf16 v[80:83], v[16:19], v[48:51], v[80:83]
	v_mfma_f32_16x16x32_bf16 v[84:87], v[8:11], v[56:59], v[84:87]
	v_mfma_f32_16x16x32_bf16 v[88:91], v[16:19], v[56:59], v[88:91]
	v_mfma_f32_16x16x32_bf16 v[92:95], v[8:11], v[64:67], v[92:95]
	v_mfma_f32_16x16x32_bf16 v[96:99], v[16:19], v[64:67], v[96:99]
	s_setprio 0
	s_setprio 1
	v_mfma_f32_16x16x32_bf16 v[100:103], v[20:23], v[36:39], 0
	v_mfma_f32_16x16x32_bf16 v[36:39], v[28:31], v[36:39], 0
	v_mfma_f32_16x16x32_bf16 v[100:103], v[24:27], v[40:43], v[100:103]
	v_mfma_f32_16x16x32_bf16 v[40:43], v[32:35], v[40:43], v[36:39]
	v_mfma_f32_16x16x32_bf16 v[36:39], v[20:23], v[44:47], 0
	v_mfma_f32_16x16x32_bf16 v[104:107], v[24:27], v[48:51], v[36:39]
	v_mfma_f32_16x16x32_bf16 v[36:39], v[28:31], v[44:47], 0
	v_mfma_f32_16x16x32_bf16 v[48:51], v[32:35], v[48:51], v[36:39]
	v_mfma_f32_16x16x32_bf16 v[36:39], v[20:23], v[52:55], 0
	v_mfma_f32_16x16x32_bf16 v[108:111], v[24:27], v[56:59], v[36:39]
	v_mfma_f32_16x16x32_bf16 v[36:39], v[28:31], v[52:55], 0
	v_mfma_f32_16x16x32_bf16 v[56:59], v[32:35], v[56:59], v[36:39]
	v_mfma_f32_16x16x32_bf16 v[36:39], v[20:23], v[60:63], 0
	v_mfma_f32_16x16x32_bf16 v[112:115], v[24:27], v[64:67], v[36:39]
	v_mfma_f32_16x16x32_bf16 v[36:39], v[28:31], v[60:63], 0
	v_mfma_f32_16x16x32_bf16 v[64:67], v[32:35], v[64:67], v[36:39]
	s_setprio 0
	s_barrier
	s_add_i32 s87, s87, s73
	s_mov_b64 s[8:9], s[16:17]
	s_mov_b32 m0, s87
	s_add_i32 s88, s87, 0x2000
	s_nop 0
	ds_read_b128 v[36:39], v141 offset:16384
	ds_read_b128 v[44:47], v141 offset:17408
	ds_read_b128 v[52:55], v141 offset:18432
	ds_read_b128 v[60:63], v141 offset:19456
	ds_read_b128 v[116:119], v141 offset:20480
	ds_read_b128 v[120:123], v141 offset:21504
	ds_read_b128 v[124:127], v141 offset:22528
	ds_read_b128 v[128:131], v141 offset:23552
	s_nop 0
	global_load_lds_dwordx4 v143, s[8:9]
	s_mov_b32 m0, s88
	s_nop 0
	global_load_lds_dwordx4 v142, s[8:9]
	s_add_u32 s8, s16, s20
	s_addc_u32 s9, s17, s21
	s_add_i32 s89, s89, s73
	s_mov_b32 m0, s89
	s_add_i32 s90, s89, 0x2000
	s_nop 0
	global_load_lds_dwordx4 v143, s[8:9]
	s_mov_b32 m0, s90
	s_nop 0
	global_load_lds_dwordx4 v142, s[8:9]
	s_waitcnt vmcnt(6)
	s_waitcnt lgkmcnt(0)
	s_barrier
	s_setprio 1
	s_waitcnt lgkmcnt(0)
	v_mfma_f32_16x16x32_bf16 v[144:147], v[4:7], v[36:39], 0
	v_mfma_f32_16x16x32_bf16 v[152:155], v[4:7], v[52:55], 0
	v_mfma_f32_16x16x32_bf16 v[160:163], v[4:7], v[116:119], 0
	v_mfma_f32_16x16x32_bf16 v[4:7], v[4:7], v[124:127], 0
	v_mfma_f32_16x16x32_bf16 v[148:151], v[12:15], v[36:39], 0
	v_mfma_f32_16x16x32_bf16 v[156:159], v[12:15], v[52:55], 0
	v_mfma_f32_16x16x32_bf16 v[164:167], v[12:15], v[116:119], 0
	v_mfma_f32_16x16x32_bf16 v[168:171], v[8:11], v[128:131], v[4:7]
	v_mfma_f32_16x16x32_bf16 v[4:7], v[12:15], v[124:127], 0
	v_mfma_f32_16x16x32_bf16 v[144:147], v[8:11], v[44:47], v[144:147]
	v_mfma_f32_16x16x32_bf16 v[148:151], v[16:19], v[44:47], v[148:151]
	v_mfma_f32_16x16x32_bf16 v[152:155], v[8:11], v[60:63], v[152:155]
	v_mfma_f32_16x16x32_bf16 v[156:159], v[16:19], v[60:63], v[156:159]
	v_mfma_f32_16x16x32_bf16 v[160:163], v[8:11], v[120:123], v[160:163]
	v_mfma_f32_16x16x32_bf16 v[164:167], v[16:19], v[120:123], v[164:167]
	v_mfma_f32_16x16x32_bf16 v[172:175], v[16:19], v[128:131], v[4:7]
	s_setprio 0
	s_setprio 1
	v_mfma_f32_16x16x32_bf16 v[4:7], v[20:23], v[36:39], 0
	v_mfma_f32_16x16x32_bf16 v[176:179], v[24:27], v[44:47], v[4:7]
	v_mfma_f32_16x16x32_bf16 v[4:7], v[28:31], v[36:39], 0
	v_mfma_f32_16x16x32_bf16 v[180:183], v[32:35], v[44:47], v[4:7]
	v_mfma_f32_16x16x32_bf16 v[4:7], v[20:23], v[52:55], 0
	v_mfma_f32_16x16x32_bf16 v[184:187], v[24:27], v[60:63], v[4:7]
	v_mfma_f32_16x16x32_bf16 v[4:7], v[28:31], v[52:55], 0
	v_mfma_f32_16x16x32_bf16 v[188:191], v[32:35], v[60:63], v[4:7]
	v_mfma_f32_16x16x32_bf16 v[4:7], v[20:23], v[116:119], 0
	v_mfma_f32_16x16x32_bf16 v[192:195], v[24:27], v[120:123], v[4:7]
	v_mfma_f32_16x16x32_bf16 v[4:7], v[28:31], v[116:119], 0
	v_mfma_f32_16x16x32_bf16 v[120:123], v[32:35], v[120:123], v[4:7]
	v_mfma_f32_16x16x32_bf16 v[4:7], v[20:23], v[124:127], 0
	v_mfma_f32_16x16x32_bf16 v[196:199], v[24:27], v[128:131], v[4:7]
	v_mfma_f32_16x16x32_bf16 v[4:7], v[28:31], v[124:127], 0
	v_mfma_f32_16x16x32_bf16 v[128:131], v[32:35], v[128:131], v[4:7]
	s_setprio 0
	s_barrier
	s_add_i32 s16, 0, 0x18000
	s_add_i32 s91, 0, 0x1c000
	v_add_u32_e32 v134, s16, v140
	v_add_u32_e32 v135, s91, v140
	ds_read_b128 v[116:119], v134
	ds_read_b128 v[124:127], v134 offset:1024
	ds_read_b128 v[200:203], v134 offset:2048
	ds_read_b128 v[204:207], v134 offset:3072
	ds_read_b128 v[216:219], v135
	ds_read_b128 v[220:223], v135 offset:1024
	ds_read_b128 v[224:227], v135 offset:2048
	ds_read_b128 v[228:231], v135 offset:3072
	s_mov_b32 m0, s76
	s_mov_b64 s[8:9], s[68:69]
	ds_read_b128 v[44:47], v141 offset:32768
	ds_read_b128 v[52:55], v141 offset:33792
	ds_read_b128 v[60:63], v141 offset:34816
	ds_read_b128 v[232:235], v141 offset:35840
	ds_read_b128 v[236:239], v141 offset:36864
	ds_read_b128 v[242:245], v141 offset:37888
	ds_read_b128 v[246:249], v141 offset:38912
	ds_read_b128 v[250:253], v141 offset:39936
	s_nop 0
	global_load_lds_dwordx4 v137, s[8:9]
	s_mov_b32 m0, s77
	s_nop 0
	global_load_lds_dwordx4 v136, s[8:9]
	s_add_u32 s8, s68, s20
	s_addc_u32 s9, s69, s21
	s_mov_b32 m0, s78
	s_nop 0
	global_load_lds_dwordx4 v137, s[8:9]
	s_mov_b32 m0, s79
	s_nop 0
	global_load_lds_dwordx4 v136, s[8:9]
	s_waitcnt vmcnt(8)
	s_waitcnt lgkmcnt(0)
	s_barrier
	s_setprio 1
	s_waitcnt lgkmcnt(0)
	v_mfma_f32_16x16x32_bf16 v[4:7], v[116:119], v[44:47], v[68:71]
	v_mfma_f32_16x16x32_bf16 v[4:7], v[124:127], v[52:55], v[4:7]
	v_mfma_f32_16x16x32_bf16 v[8:11], v[200:203], v[44:47], v[72:75]
	v_mfma_f32_16x16x32_bf16 v[8:11], v[204:207], v[52:55], v[8:11]
	v_mfma_f32_16x16x32_bf16 v[12:15], v[116:119], v[60:63], v[76:79]
	v_mfma_f32_16x16x32_bf16 v[12:15], v[124:127], v[232:235], v[12:15]
	v_mfma_f32_16x16x32_bf16 v[16:19], v[200:203], v[60:63], v[80:83]
	v_mfma_f32_16x16x32_bf16 v[16:19], v[204:207], v[232:235], v[16:19]
	v_mfma_f32_16x16x32_bf16 v[20:23], v[116:119], v[236:239], v[84:87]
	v_mfma_f32_16x16x32_bf16 v[20:23], v[124:127], v[242:245], v[20:23]
	v_mfma_f32_16x16x32_bf16 v[24:27], v[200:203], v[236:239], v[88:91]
	v_mfma_f32_16x16x32_bf16 v[24:27], v[204:207], v[242:245], v[24:27]
	v_mfma_f32_16x16x32_bf16 v[28:31], v[116:119], v[246:249], v[92:95]
	v_mfma_f32_16x16x32_bf16 v[28:31], v[124:127], v[250:253], v[28:31]
	v_mfma_f32_16x16x32_bf16 v[32:35], v[200:203], v[246:249], v[96:99]
	v_mfma_f32_16x16x32_bf16 v[32:35], v[204:207], v[250:253], v[32:35]
	s_setprio 0
	s_setprio 1
	v_mfma_f32_16x16x32_bf16 v[36:39], v[216:219], v[44:47], v[100:103]
	v_mfma_f32_16x16x32_bf16 v[40:43], v[224:227], v[44:47], v[40:43]
	v_mfma_f32_16x16x32_bf16 v[36:39], v[220:223], v[52:55], v[36:39]
	v_mfma_f32_16x16x32_bf16 v[40:43], v[228:231], v[52:55], v[40:43]
	v_mfma_f32_16x16x32_bf16 v[44:47], v[216:219], v[60:63], v[104:107]
	v_mfma_f32_16x16x32_bf16 v[48:51], v[224:227], v[60:63], v[48:51]
	v_mfma_f32_16x16x32_bf16 v[52:55], v[216:219], v[236:239], v[108:111]
	v_mfma_f32_16x16x32_bf16 v[56:59], v[224:227], v[236:239], v[56:59]
	v_mfma_f32_16x16x32_bf16 v[60:63], v[216:219], v[246:249], v[112:115]
	v_mfma_f32_16x16x32_bf16 v[64:67], v[224:227], v[246:249], v[64:67]
	v_mfma_f32_16x16x32_bf16 v[44:47], v[220:223], v[232:235], v[44:47]
	v_mfma_f32_16x16x32_bf16 v[48:51], v[228:231], v[232:235], v[48:51]
	v_mfma_f32_16x16x32_bf16 v[52:55], v[220:223], v[242:245], v[52:55]
	v_mfma_f32_16x16x32_bf16 v[56:59], v[228:231], v[242:245], v[56:59]
	v_mfma_f32_16x16x32_bf16 v[60:63], v[220:223], v[250:253], v[60:63]
	v_mfma_f32_16x16x32_bf16 v[64:67], v[228:231], v[250:253], v[64:67]
	s_setprio 0
	s_barrier
	s_add_i32 s68, s16, s73
	s_mov_b64 s[8:9], s[18:19]
	s_mov_b32 m0, s68
	s_add_i32 s69, s68, 0x2000
	ds_read_b128 v[104:107], v141 offset:49152
	ds_read_b128 v[108:111], v141 offset:50176
	ds_read_b128 v[112:115], v141 offset:51200
	ds_read_b128 v[232:235], v141 offset:52224
	ds_read_b128 v[236:239], v141 offset:53248
	ds_read_b128 v[242:245], v141 offset:54272
	ds_read_b128 v[246:249], v141 offset:55296
	ds_read_b128 v[250:253], v141 offset:56320
	s_nop 0
	global_load_lds_dwordx4 v143, s[8:9]
	s_mov_b32 m0, s69
	s_nop 0
	global_load_lds_dwordx4 v142, s[8:9]
	s_add_u32 s8, s18, s20
	s_addc_u32 s9, s19, s21
	s_add_i32 s91, s91, s73
	s_mov_b32 m0, s91
	s_add_i32 s92, s91, 0x2000
	s_nop 0
	global_load_lds_dwordx4 v143, s[8:9]
	s_mov_b32 m0, s92
	s_nop 0
	global_load_lds_dwordx4 v142, s[8:9]
	s_waitcnt vmcnt(6)
	s_waitcnt lgkmcnt(0)
	s_barrier
	s_setprio 1
	s_waitcnt lgkmcnt(0)
	v_mfma_f32_16x16x32_bf16 v[68:71], v[116:119], v[104:107], v[144:147]
	v_mfma_f32_16x16x32_bf16 v[68:71], v[124:127], v[108:111], v[68:71]
	v_mfma_f32_16x16x32_bf16 v[72:75], v[200:203], v[104:107], v[148:151]
	v_mfma_f32_16x16x32_bf16 v[72:75], v[204:207], v[108:111], v[72:75]
	v_mfma_f32_16x16x32_bf16 v[76:79], v[116:119], v[112:115], v[152:155]
	v_mfma_f32_16x16x32_bf16 v[76:79], v[124:127], v[232:235], v[76:79]
	v_mfma_f32_16x16x32_bf16 v[80:83], v[200:203], v[112:115], v[156:159]
	v_mfma_f32_16x16x32_bf16 v[80:83], v[204:207], v[232:235], v[80:83]
	v_mfma_f32_16x16x32_bf16 v[84:87], v[116:119], v[236:239], v[160:163]
	v_mfma_f32_16x16x32_bf16 v[84:87], v[124:127], v[242:245], v[84:87]
	v_mfma_f32_16x16x32_bf16 v[88:91], v[200:203], v[236:239], v[164:167]
	v_mfma_f32_16x16x32_bf16 v[88:91], v[204:207], v[242:245], v[88:91]
	v_mfma_f32_16x16x32_bf16 v[92:95], v[116:119], v[246:249], v[168:171]
	v_mfma_f32_16x16x32_bf16 v[92:95], v[124:127], v[250:253], v[92:95]
	v_mfma_f32_16x16x32_bf16 v[96:99], v[200:203], v[246:249], v[172:175]
	v_mfma_f32_16x16x32_bf16 v[96:99], v[204:207], v[250:253], v[96:99]
	s_setprio 0
	s_setprio 1
	v_mfma_f32_16x16x32_bf16 v[100:103], v[216:219], v[104:107], v[176:179]
	v_mfma_f32_16x16x32_bf16 v[104:107], v[224:227], v[104:107], v[180:183]
	v_mfma_f32_16x16x32_bf16 v[100:103], v[220:223], v[108:111], v[100:103]
	v_mfma_f32_16x16x32_bf16 v[104:107], v[228:231], v[108:111], v[104:107]
	v_mfma_f32_16x16x32_bf16 v[108:111], v[216:219], v[112:115], v[184:187]
	v_mfma_f32_16x16x32_bf16 v[112:115], v[224:227], v[112:115], v[188:191]
	v_mfma_f32_16x16x32_bf16 v[116:119], v[216:219], v[236:239], v[192:195]
	v_mfma_f32_16x16x32_bf16 v[120:123], v[224:227], v[236:239], v[120:123]
	v_mfma_f32_16x16x32_bf16 v[124:127], v[216:219], v[246:249], v[196:199]
	v_mfma_f32_16x16x32_bf16 v[128:131], v[224:227], v[246:249], v[128:131]
	v_mfma_f32_16x16x32_bf16 v[108:111], v[220:223], v[232:235], v[108:111]
	v_mfma_f32_16x16x32_bf16 v[112:115], v[228:231], v[232:235], v[112:115]
	v_mfma_f32_16x16x32_bf16 v[116:119], v[220:223], v[242:245], v[116:119]
	v_mfma_f32_16x16x32_bf16 v[120:123], v[228:231], v[242:245], v[120:123]
	v_mfma_f32_16x16x32_bf16 v[124:127], v[220:223], v[250:253], v[124:127]
	v_mfma_f32_16x16x32_bf16 v[128:131], v[228:231], v[250:253], v[128:131]
	s_setprio 0
	s_barrier
	s_andn2_b64 vcc, exec, s[60:61]
	s_cbranch_vccnz .LBB0_1031
	s_add_u32 s93, s64, 0x200
	s_addc_u32 s94, s65, 0
	s_add_u32 s66, s66, 0x200
	s_addc_u32 s67, s67, 0
	s_mov_b32 s95, 4
	.p2align	6
	s_nop 0
	s_nop 0
	s_nop 0
	s_nop 0
	s_nop 0
	s_nop 0
	s_nop 0
	s_nop 0
	s_nop 0
	s_nop 0
	s_nop 0
	s_nop 0

.LBB0_1154:
	s_add_u32 s18, s52, 0x100
	s_addc_u32 s19, s53, 0
	s_add_u32 s16, s20, 0x100
	s_addc_u32 s17, s21, 0
	s_and_b64 s[8:9], s[46:47], exec
	s_cselect_b32 s17, s27, s17
	s_cselect_b32 s16, s26, s16
	s_add_i32 s72, 0, 0x10000
	s_and_b64 s[8:9], s[46:47], exec
	s_cselect_b32 s43, s51, s19
	s_cselect_b32 s42, s50, s18
	s_add_i32 s76, 0, 0x14000
	v_add_u32_e32 v132, s72, v243
	v_add_u32_e32 v133, s76, v243
	ds_read_b128 v[4:7], v132
	ds_read_b128 v[8:11], v132 offset:1024
	ds_read_b128 v[12:15], v132 offset:2048
	ds_read_b128 v[16:19], v132 offset:3072
	ds_read_b128 v[20:23], v133
	ds_read_b128 v[24:27], v133 offset:1024
	ds_read_b128 v[28:31], v133 offset:2048
	ds_read_b128 v[32:35], v133 offset:3072
	s_add_u32 s8, s52, 0x80
	s_addc_u32 s9, s53, 0
	s_add_i32 s66, s58, 0x8000
	s_add_i32 s67, s58, 0xa000
	s_mov_b64 s[18:19], s[8:9]
	s_mov_b32 m0, s66
	s_add_u32 s8, s8, s28
	ds_read_b128 v[36:39], v244 offset:8192
	ds_read_b128 v[40:43], v244 offset:9216
	ds_read_b128 v[44:47], v244 offset:10240
	ds_read_b128 v[48:51], v244 offset:11264
	ds_read_b128 v[52:55], v244 offset:12288
	ds_read_b128 v[56:59], v244 offset:13312
	ds_read_b128 v[60:63], v244 offset:14336
	ds_read_b128 v[64:67], v244 offset:15360
	s_addc_u32 s9, s9, s29
	global_load_lds_dwordx4 v238, s[18:19]
	s_mov_b32 m0, s67
	s_add_i32 s68, s58, 0xc000
	global_load_lds_dwordx4 v2, s[18:19]
	s_mov_b32 m0, s68
	s_add_i32 s69, s58, 0xe000
	s_add_u32 s18, s16, 0x80
	global_load_lds_dwordx4 v238, s[8:9]
	s_mov_b32 m0, s69
	s_addc_u32 s19, s17, 0
	global_load_lds_dwordx4 v2, s[8:9]
	s_waitcnt vmcnt(8)
	s_waitcnt lgkmcnt(0)
	s_barrier
	s_setprio 1
	s_waitcnt lgkmcnt(0)
	v_mfma_f32_16x16x32_bf16 v[68:71], v[4:7], v[36:39], 0
	v_mfma_f32_16x16x32_bf16 v[72:75], v[12:15], v[36:39], 0
	v_mfma_f32_16x16x32_bf16 v[76:79], v[4:7], v[44:47], 0
	v_mfma_f32_16x16x32_bf16 v[80:83], v[12:15], v[44:47], 0
	v_mfma_f32_16x16x32_bf16 v[84:87], v[4:7], v[52:55], 0
	v_mfma_f32_16x16x32_bf16 v[88:91], v[12:15], v[52:55], 0
	v_mfma_f32_16x16x32_bf16 v[92:95], v[4:7], v[60:63], 0
	v_mfma_f32_16x16x32_bf16 v[96:99], v[12:15], v[60:63], 0
	v_mfma_f32_16x16x32_bf16 v[68:71], v[8:11], v[40:43], v[68:71]
	v_mfma_f32_16x16x32_bf16 v[72:75], v[16:19], v[40:43], v[72:75]
	v_mfma_f32_16x16x32_bf16 v[76:79], v[8:11], v[48:51], v[76:79]
	v_mfma_f32_16x16x32_bf16 v[80:83], v[16:19], v[48:51], v[80:83]
	v_mfma_f32_16x16x32_bf16 v[84:87], v[8:11], v[56:59], v[84:87]
	v_mfma_f32_16x16x32_bf16 v[88:91], v[16:19], v[56:59], v[88:91]
	v_mfma_f32_16x16x32_bf16 v[92:95], v[8:11], v[64:67], v[92:95]
	v_mfma_f32_16x16x32_bf16 v[96:99], v[16:19], v[64:67], v[96:99]
	s_setprio 0
	s_setprio 1
	v_mfma_f32_16x16x32_bf16 v[100:103], v[20:23], v[36:39], 0
	v_mfma_f32_16x16x32_bf16 v[36:39], v[28:31], v[36:39], 0
	v_mfma_f32_16x16x32_bf16 v[100:103], v[24:27], v[40:43], v[100:103]
	v_mfma_f32_16x16x32_bf16 v[40:43], v[32:35], v[40:43], v[36:39]
	v_mfma_f32_16x16x32_bf16 v[36:39], v[20:23], v[44:47], 0
	v_mfma_f32_16x16x32_bf16 v[104:107], v[24:27], v[48:51], v[36:39]
	v_mfma_f32_16x16x32_bf16 v[36:39], v[28:31], v[44:47], 0
	v_mfma_f32_16x16x32_bf16 v[48:51], v[32:35], v[48:51], v[36:39]
	v_mfma_f32_16x16x32_bf16 v[36:39], v[20:23], v[52:55], 0
	v_mfma_f32_16x16x32_bf16 v[108:111], v[24:27], v[56:59], v[36:39]
	v_mfma_f32_16x16x32_bf16 v[36:39], v[28:31], v[52:55], 0
	v_mfma_f32_16x16x32_bf16 v[56:59], v[32:35], v[56:59], v[36:39]
	v_mfma_f32_16x16x32_bf16 v[36:39], v[20:23], v[60:63], 0
	v_mfma_f32_16x16x32_bf16 v[112:115], v[24:27], v[64:67], v[36:39]
	v_mfma_f32_16x16x32_bf16 v[36:39], v[28:31], v[60:63], 0
	v_mfma_f32_16x16x32_bf16 v[64:67], v[32:35], v[64:67], v[36:39]
	s_setprio 0
	s_barrier
	s_add_i32 s72, s72, s57
	s_mov_b64 s[8:9], s[16:17]
	s_mov_b32 m0, s72
	s_add_i32 s73, s72, 0x2000
	s_nop 0
	ds_read_b128 v[36:39], v244 offset:24576
	ds_read_b128 v[44:47], v244 offset:25600
	ds_read_b128 v[52:55], v244 offset:26624
	ds_read_b128 v[60:63], v244 offset:27648
	ds_read_b128 v[116:119], v244 offset:28672
	ds_read_b128 v[120:123], v244 offset:29696
	ds_read_b128 v[124:127], v244 offset:30720
	ds_read_b128 v[128:131], v244 offset:31744
	s_nop 0
	global_load_lds_dwordx4 v246, s[8:9]
	s_mov_b32 m0, s73
	s_nop 0
	global_load_lds_dwordx4 v245, s[8:9]
	s_add_u32 s8, s16, s28
	s_addc_u32 s9, s17, s29
	s_add_i32 s76, s76, s57
	s_mov_b32 m0, s76
	s_add_i32 s77, s76, 0x2000
	s_nop 0
	global_load_lds_dwordx4 v246, s[8:9]
	s_mov_b32 m0, s77
	s_nop 0
	global_load_lds_dwordx4 v245, s[8:9]
	s_waitcnt vmcnt(6)
	s_waitcnt lgkmcnt(0)
	s_barrier
	s_setprio 1
	s_waitcnt lgkmcnt(0)
	v_mfma_f32_16x16x32_bf16 v[134:137], v[4:7], v[36:39], 0
	v_mfma_f32_16x16x32_bf16 v[144:147], v[4:7], v[52:55], 0
	v_mfma_f32_16x16x32_bf16 v[152:155], v[4:7], v[116:119], 0
	v_mfma_f32_16x16x32_bf16 v[4:7], v[4:7], v[124:127], 0
	v_mfma_f32_16x16x32_bf16 v[140:143], v[12:15], v[36:39], 0
	v_mfma_f32_16x16x32_bf16 v[148:151], v[12:15], v[52:55], 0
	v_mfma_f32_16x16x32_bf16 v[156:159], v[12:15], v[116:119], 0
	v_mfma_f32_16x16x32_bf16 v[160:163], v[8:11], v[128:131], v[4:7]
	v_mfma_f32_16x16x32_bf16 v[4:7], v[12:15], v[124:127], 0
	v_mfma_f32_16x16x32_bf16 v[136:139], v[8:11], v[44:47], v[134:137]
	v_mfma_f32_16x16x32_bf16 v[140:143], v[16:19], v[44:47], v[140:143]
	v_mfma_f32_16x16x32_bf16 v[144:147], v[8:11], v[60:63], v[144:147]
	v_mfma_f32_16x16x32_bf16 v[148:151], v[16:19], v[60:63], v[148:151]
	v_mfma_f32_16x16x32_bf16 v[152:155], v[8:11], v[120:123], v[152:155]
	v_mfma_f32_16x16x32_bf16 v[156:159], v[16:19], v[120:123], v[156:159]
	v_mfma_f32_16x16x32_bf16 v[164:167], v[16:19], v[128:131], v[4:7]
	s_setprio 0
	s_setprio 1
	v_mfma_f32_16x16x32_bf16 v[4:7], v[20:23], v[36:39], 0
	v_mfma_f32_16x16x32_bf16 v[168:171], v[24:27], v[44:47], v[4:7]
	v_mfma_f32_16x16x32_bf16 v[4:7], v[28:31], v[36:39], 0
	v_mfma_f32_16x16x32_bf16 v[172:175], v[32:35], v[44:47], v[4:7]
	v_mfma_f32_16x16x32_bf16 v[4:7], v[20:23], v[52:55], 0
	v_mfma_f32_16x16x32_bf16 v[176:179], v[24:27], v[60:63], v[4:7]
	v_mfma_f32_16x16x32_bf16 v[4:7], v[28:31], v[52:55], 0
	v_mfma_f32_16x16x32_bf16 v[180:183], v[32:35], v[60:63], v[4:7]
	v_mfma_f32_16x16x32_bf16 v[4:7], v[20:23], v[116:119], 0
	v_mfma_f32_16x16x32_bf16 v[184:187], v[24:27], v[120:123], v[4:7]
	v_mfma_f32_16x16x32_bf16 v[4:7], v[28:31], v[116:119], 0
	v_mfma_f32_16x16x32_bf16 v[120:123], v[32:35], v[120:123], v[4:7]
	v_mfma_f32_16x16x32_bf16 v[4:7], v[20:23], v[124:127], 0
	v_mfma_f32_16x16x32_bf16 v[188:191], v[24:27], v[128:131], v[4:7]
	v_mfma_f32_16x16x32_bf16 v[4:7], v[28:31], v[124:127], 0
	v_mfma_f32_16x16x32_bf16 v[128:131], v[32:35], v[128:131], v[4:7]
	s_setprio 0
	s_barrier
	s_add_i32 s16, 0, 0x18000
	s_add_i32 s78, 0, 0x1c000
	v_add_u32_e32 v134, s16, v243
	v_add_u32_e32 v135, s78, v243
	ds_read_b128 v[116:119], v134
	ds_read_b128 v[124:127], v134 offset:1024
	ds_read_b128 v[192:195], v134 offset:2048
	ds_read_b128 v[196:199], v134 offset:3072
	ds_read_b128 v[200:203], v135
	ds_read_b128 v[204:207], v135 offset:1024
	ds_read_b128 v[208:211], v135 offset:2048
	ds_read_b128 v[216:219], v135 offset:3072
	s_mov_b32 m0, s58
	s_mov_b64 s[8:9], s[42:43]
	ds_read_b128 v[44:47], v244 offset:40960
	ds_read_b128 v[52:55], v244 offset:41984
	ds_read_b128 v[60:63], v244 offset:43008
	ds_read_b128 v[220:223], v244 offset:44032
	ds_read_b128 v[224:227], v244 offset:45056
	ds_read_b128 v[228:231], v244 offset:46080
	ds_read_b128 v[232:235], v244 offset:47104
	ds_read_b128 v[248:251], v244 offset:48128
	s_nop 0
	global_load_lds_dwordx4 v238, s[8:9]
	s_mov_b32 m0, s59
	s_nop 0
	global_load_lds_dwordx4 v2, s[8:9]
	s_add_u32 s8, s42, s28
	s_addc_u32 s9, s43, s29
	s_mov_b32 m0, s60
	s_nop 0
	global_load_lds_dwordx4 v238, s[8:9]
	s_mov_b32 m0, s61
	s_nop 0
	global_load_lds_dwordx4 v2, s[8:9]
	s_waitcnt vmcnt(8)
	s_waitcnt lgkmcnt(0)
	s_barrier
	s_setprio 1
	s_waitcnt lgkmcnt(0)
	v_mfma_f32_16x16x32_bf16 v[4:7], v[116:119], v[44:47], v[68:71]
	v_mfma_f32_16x16x32_bf16 v[4:7], v[124:127], v[52:55], v[4:7]
	v_mfma_f32_16x16x32_bf16 v[8:11], v[192:195], v[44:47], v[72:75]
	v_mfma_f32_16x16x32_bf16 v[8:11], v[196:199], v[52:55], v[8:11]
	v_mfma_f32_16x16x32_bf16 v[12:15], v[116:119], v[60:63], v[76:79]
	v_mfma_f32_16x16x32_bf16 v[12:15], v[124:127], v[220:223], v[12:15]
	v_mfma_f32_16x16x32_bf16 v[16:19], v[192:195], v[60:63], v[80:83]
	v_mfma_f32_16x16x32_bf16 v[16:19], v[196:199], v[220:223], v[16:19]
	v_mfma_f32_16x16x32_bf16 v[20:23], v[116:119], v[224:227], v[84:87]
	v_mfma_f32_16x16x32_bf16 v[20:23], v[124:127], v[228:231], v[20:23]
	v_mfma_f32_16x16x32_bf16 v[24:27], v[192:195], v[224:227], v[88:91]
	v_mfma_f32_16x16x32_bf16 v[24:27], v[196:199], v[228:231], v[24:27]
	v_mfma_f32_16x16x32_bf16 v[28:31], v[116:119], v[232:235], v[92:95]
	v_mfma_f32_16x16x32_bf16 v[28:31], v[124:127], v[248:251], v[28:31]
	v_mfma_f32_16x16x32_bf16 v[32:35], v[192:195], v[232:235], v[96:99]
	v_mfma_f32_16x16x32_bf16 v[32:35], v[196:199], v[248:251], v[32:35]
	s_setprio 0
	s_setprio 1
	v_mfma_f32_16x16x32_bf16 v[36:39], v[200:203], v[44:47], v[100:103]
	v_mfma_f32_16x16x32_bf16 v[40:43], v[208:211], v[44:47], v[40:43]
	v_mfma_f32_16x16x32_bf16 v[36:39], v[204:207], v[52:55], v[36:39]
	v_mfma_f32_16x16x32_bf16 v[40:43], v[216:219], v[52:55], v[40:43]
	v_mfma_f32_16x16x32_bf16 v[44:47], v[200:203], v[60:63], v[104:107]
	v_mfma_f32_16x16x32_bf16 v[48:51], v[208:211], v[60:63], v[48:51]
	v_mfma_f32_16x16x32_bf16 v[52:55], v[200:203], v[224:227], v[108:111]
	v_mfma_f32_16x16x32_bf16 v[56:59], v[208:211], v[224:227], v[56:59]
	v_mfma_f32_16x16x32_bf16 v[60:63], v[200:203], v[232:235], v[112:115]
	v_mfma_f32_16x16x32_bf16 v[64:67], v[208:211], v[232:235], v[64:67]
	v_mfma_f32_16x16x32_bf16 v[44:47], v[204:207], v[220:223], v[44:47]
	v_mfma_f32_16x16x32_bf16 v[48:51], v[216:219], v[220:223], v[48:51]
	v_mfma_f32_16x16x32_bf16 v[52:55], v[204:207], v[228:231], v[52:55]
	v_mfma_f32_16x16x32_bf16 v[56:59], v[216:219], v[228:231], v[56:59]
	v_mfma_f32_16x16x32_bf16 v[60:63], v[204:207], v[248:251], v[60:63]
	v_mfma_f32_16x16x32_bf16 v[64:67], v[216:219], v[248:251], v[64:67]
	s_setprio 0
	s_barrier
	s_add_i32 s42, s16, s57
	s_mov_b64 s[8:9], s[18:19]
	s_mov_b32 m0, s42
	s_add_i32 s43, s42, 0x2000
	ds_read_b128 v[104:107], v244 offset:57344
	ds_read_b128 v[108:111], v244 offset:58368
	ds_read_b128 v[112:115], v244 offset:59392
	ds_read_b128 v[220:223], v244 offset:60416
	ds_read_b128 v[224:227], v244 offset:61440
	ds_read_b128 v[228:231], v244 offset:62464
	ds_read_b128 v[232:235], v244 offset:63488
	ds_read_b128 v[248:251], v244 offset:64512
	s_nop 0
	global_load_lds_dwordx4 v246, s[8:9]
	s_mov_b32 m0, s43
	s_nop 0
	global_load_lds_dwordx4 v245, s[8:9]
	s_add_u32 s8, s18, s28
	s_addc_u32 s9, s19, s29
	s_add_i32 s78, s78, s57
	s_mov_b32 m0, s78
	s_add_i32 s79, s78, 0x2000
	s_nop 0
	global_load_lds_dwordx4 v246, s[8:9]
	s_mov_b32 m0, s79
	s_nop 0
	global_load_lds_dwordx4 v245, s[8:9]
	s_waitcnt vmcnt(6)
	s_waitcnt lgkmcnt(0)
	s_barrier
	s_setprio 1
	s_waitcnt lgkmcnt(0)
	v_mfma_f32_16x16x32_bf16 v[68:71], v[116:119], v[104:107], v[136:139]
	v_mfma_f32_16x16x32_bf16 v[68:71], v[124:127], v[108:111], v[68:71]
	v_mfma_f32_16x16x32_bf16 v[72:75], v[192:195], v[104:107], v[140:143]
	v_mfma_f32_16x16x32_bf16 v[72:75], v[196:199], v[108:111], v[72:75]
	v_mfma_f32_16x16x32_bf16 v[76:79], v[116:119], v[112:115], v[144:147]
	v_mfma_f32_16x16x32_bf16 v[76:79], v[124:127], v[220:223], v[76:79]
	v_mfma_f32_16x16x32_bf16 v[80:83], v[192:195], v[112:115], v[148:151]
	v_mfma_f32_16x16x32_bf16 v[80:83], v[196:199], v[220:223], v[80:83]
	v_mfma_f32_16x16x32_bf16 v[84:87], v[116:119], v[224:227], v[152:155]
	v_mfma_f32_16x16x32_bf16 v[84:87], v[124:127], v[228:231], v[84:87]
	v_mfma_f32_16x16x32_bf16 v[88:91], v[192:195], v[224:227], v[156:159]
	v_mfma_f32_16x16x32_bf16 v[88:91], v[196:199], v[228:231], v[88:91]
	v_mfma_f32_16x16x32_bf16 v[92:95], v[116:119], v[232:235], v[160:163]
	v_mfma_f32_16x16x32_bf16 v[92:95], v[124:127], v[248:251], v[92:95]
	v_mfma_f32_16x16x32_bf16 v[96:99], v[192:195], v[232:235], v[164:167]
	v_mfma_f32_16x16x32_bf16 v[96:99], v[196:199], v[248:251], v[96:99]
	s_setprio 0
	s_setprio 1
	v_mfma_f32_16x16x32_bf16 v[100:103], v[200:203], v[104:107], v[168:171]
	v_mfma_f32_16x16x32_bf16 v[104:107], v[208:211], v[104:107], v[172:175]
	v_mfma_f32_16x16x32_bf16 v[100:103], v[204:207], v[108:111], v[100:103]
	v_mfma_f32_16x16x32_bf16 v[104:107], v[216:219], v[108:111], v[104:107]
	v_mfma_f32_16x16x32_bf16 v[108:111], v[200:203], v[112:115], v[176:179]
	v_mfma_f32_16x16x32_bf16 v[112:115], v[208:211], v[112:115], v[180:183]
	v_mfma_f32_16x16x32_bf16 v[116:119], v[200:203], v[224:227], v[184:187]
	v_mfma_f32_16x16x32_bf16 v[120:123], v[208:211], v[224:227], v[120:123]
	v_mfma_f32_16x16x32_bf16 v[124:127], v[200:203], v[232:235], v[188:191]
	v_mfma_f32_16x16x32_bf16 v[128:131], v[208:211], v[232:235], v[128:131]
	v_mfma_f32_16x16x32_bf16 v[108:111], v[204:207], v[220:223], v[108:111]
	v_mfma_f32_16x16x32_bf16 v[112:115], v[216:219], v[220:223], v[112:115]
	v_mfma_f32_16x16x32_bf16 v[116:119], v[204:207], v[228:231], v[116:119]
	v_mfma_f32_16x16x32_bf16 v[120:123], v[216:219], v[228:231], v[120:123]
	v_mfma_f32_16x16x32_bf16 v[124:127], v[204:207], v[248:251], v[124:127]
	v_mfma_f32_16x16x32_bf16 v[128:131], v[216:219], v[248:251], v[128:131]
	s_setprio 0
	s_barrier
	s_andn2_b64 vcc, exec, s[48:49]
	s_cbranch_vccnz .LBB0_1157
	s_add_u32 s80, s20, 0x200
	s_addc_u32 s81, s21, 0
	s_add_u32 s52, s52, 0x200
	s_addc_u32 s53, s53, 0
	s_mov_b32 s82, 4
	.p2align	6
	s_nop 0
	s_nop 0
	s_nop 0
	s_nop 0
	s_nop 0
	s_nop 0
	s_nop 0
	s_nop 0
	s_nop 0
	s_nop 0
	s_nop 0
	s_nop 0

.LBB0_1174:
	s_add_u32 s18, s50, 0x100
	s_addc_u32 s19, s51, 0
	s_add_u32 s16, s26, 0x100
	s_addc_u32 s17, s27, 0
	s_and_b64 s[8:9], s[46:47], exec
	s_cselect_b32 s17, s21, s17
	s_cselect_b32 s16, s20, s16
	s_add_i32 s68, 0, 0x10000
	s_and_b64 s[8:9], s[46:47], exec
	s_cselect_b32 s43, s41, s19
	s_cselect_b32 s42, s40, s18
	s_add_i32 s72, 0, 0x14000
	v_add_u32_e32 v132, s68, v243
	v_add_u32_e32 v133, s72, v243
	ds_read_b128 v[4:7], v132
	ds_read_b128 v[8:11], v132 offset:1024
	ds_read_b128 v[12:15], v132 offset:2048
	ds_read_b128 v[16:19], v132 offset:3072
	ds_read_b128 v[20:23], v133
	ds_read_b128 v[24:27], v133 offset:1024
	ds_read_b128 v[28:31], v133 offset:2048
	ds_read_b128 v[32:35], v133 offset:3072
	s_add_u32 s8, s50, 0x80
	s_addc_u32 s9, s51, 0
	s_add_i32 s64, s53, 0x8000
	s_add_i32 s65, s53, 0xa000
	s_mov_b64 s[18:19], s[8:9]
	s_mov_b32 m0, s64
	s_add_u32 s8, s8, s28
	ds_read_b128 v[36:39], v244
	ds_read_b128 v[40:43], v244 offset:1024
	ds_read_b128 v[44:47], v244 offset:2048
	ds_read_b128 v[48:51], v244 offset:3072
	ds_read_b128 v[52:55], v244 offset:4096
	ds_read_b128 v[56:59], v244 offset:5120
	ds_read_b128 v[60:63], v244 offset:6144
	ds_read_b128 v[64:67], v244 offset:7168
	s_addc_u32 s9, s9, s29
	global_load_lds_dwordx4 v238, s[18:19]
	s_mov_b32 m0, s65
	s_add_i32 s66, s53, 0xc000
	global_load_lds_dwordx4 v2, s[18:19]
	s_mov_b32 m0, s66
	s_add_i32 s67, s53, 0xe000
	s_add_u32 s18, s16, 0x80
	global_load_lds_dwordx4 v238, s[8:9]
	s_mov_b32 m0, s67
	s_addc_u32 s19, s17, 0
	global_load_lds_dwordx4 v2, s[8:9]
	s_waitcnt vmcnt(8)
	s_waitcnt lgkmcnt(0)
	s_barrier
	s_setprio 1
	s_waitcnt lgkmcnt(0)
	v_mfma_f32_16x16x32_bf16 v[68:71], v[4:7], v[36:39], 0
	v_mfma_f32_16x16x32_bf16 v[72:75], v[12:15], v[36:39], 0
	v_mfma_f32_16x16x32_bf16 v[76:79], v[4:7], v[44:47], 0
	v_mfma_f32_16x16x32_bf16 v[80:83], v[12:15], v[44:47], 0
	v_mfma_f32_16x16x32_bf16 v[84:87], v[4:7], v[52:55], 0
	v_mfma_f32_16x16x32_bf16 v[88:91], v[12:15], v[52:55], 0
	v_mfma_f32_16x16x32_bf16 v[92:95], v[4:7], v[60:63], 0
	v_mfma_f32_16x16x32_bf16 v[96:99], v[12:15], v[60:63], 0
	v_mfma_f32_16x16x32_bf16 v[68:71], v[8:11], v[40:43], v[68:71]
	v_mfma_f32_16x16x32_bf16 v[72:75], v[16:19], v[40:43], v[72:75]
	v_mfma_f32_16x16x32_bf16 v[76:79], v[8:11], v[48:51], v[76:79]
	v_mfma_f32_16x16x32_bf16 v[80:83], v[16:19], v[48:51], v[80:83]
	v_mfma_f32_16x16x32_bf16 v[84:87], v[8:11], v[56:59], v[84:87]
	v_mfma_f32_16x16x32_bf16 v[88:91], v[16:19], v[56:59], v[88:91]
	v_mfma_f32_16x16x32_bf16 v[92:95], v[8:11], v[64:67], v[92:95]
	v_mfma_f32_16x16x32_bf16 v[96:99], v[16:19], v[64:67], v[96:99]
	s_setprio 0
	s_setprio 1
	v_mfma_f32_16x16x32_bf16 v[100:103], v[20:23], v[36:39], 0
	v_mfma_f32_16x16x32_bf16 v[36:39], v[28:31], v[36:39], 0
	v_mfma_f32_16x16x32_bf16 v[100:103], v[24:27], v[40:43], v[100:103]
	v_mfma_f32_16x16x32_bf16 v[40:43], v[32:35], v[40:43], v[36:39]
	v_mfma_f32_16x16x32_bf16 v[36:39], v[20:23], v[44:47], 0
	v_mfma_f32_16x16x32_bf16 v[104:107], v[24:27], v[48:51], v[36:39]
	v_mfma_f32_16x16x32_bf16 v[36:39], v[28:31], v[44:47], 0
	v_mfma_f32_16x16x32_bf16 v[48:51], v[32:35], v[48:51], v[36:39]
	v_mfma_f32_16x16x32_bf16 v[36:39], v[20:23], v[52:55], 0
	v_mfma_f32_16x16x32_bf16 v[108:111], v[24:27], v[56:59], v[36:39]
	v_mfma_f32_16x16x32_bf16 v[36:39], v[28:31], v[52:55], 0
	v_mfma_f32_16x16x32_bf16 v[56:59], v[32:35], v[56:59], v[36:39]
	v_mfma_f32_16x16x32_bf16 v[36:39], v[20:23], v[60:63], 0
	v_mfma_f32_16x16x32_bf16 v[112:115], v[24:27], v[64:67], v[36:39]
	v_mfma_f32_16x16x32_bf16 v[36:39], v[28:31], v[60:63], 0
	v_mfma_f32_16x16x32_bf16 v[64:67], v[32:35], v[64:67], v[36:39]
	s_setprio 0
	s_barrier
	s_add_i32 s68, s68, s52
	s_mov_b64 s[8:9], s[16:17]
	s_mov_b32 m0, s68
	s_add_i32 s69, s68, 0x2000
	s_nop 0
	ds_read_b128 v[36:39], v244 offset:16384
	ds_read_b128 v[44:47], v244 offset:17408
	ds_read_b128 v[52:55], v244 offset:18432
	ds_read_b128 v[60:63], v244 offset:19456
	ds_read_b128 v[116:119], v244 offset:20480
	ds_read_b128 v[120:123], v244 offset:21504
	ds_read_b128 v[124:127], v244 offset:22528
	ds_read_b128 v[128:131], v244 offset:23552
	s_nop 0
	global_load_lds_dwordx4 v246, s[8:9]
	s_mov_b32 m0, s69
	s_nop 0
	global_load_lds_dwordx4 v245, s[8:9]
	s_add_u32 s8, s16, s28
	s_addc_u32 s9, s17, s29
	s_add_i32 s72, s72, s52
	s_mov_b32 m0, s72
	s_add_i32 s73, s72, 0x2000
	s_nop 0
	global_load_lds_dwordx4 v246, s[8:9]
	s_mov_b32 m0, s73
	s_nop 0
	global_load_lds_dwordx4 v245, s[8:9]
	s_waitcnt vmcnt(6)
	s_waitcnt lgkmcnt(0)
	s_barrier
	s_setprio 1
	s_waitcnt lgkmcnt(0)
	v_mfma_f32_16x16x32_bf16 v[134:137], v[4:7], v[36:39], 0
	v_mfma_f32_16x16x32_bf16 v[144:147], v[4:7], v[52:55], 0
	v_mfma_f32_16x16x32_bf16 v[152:155], v[4:7], v[116:119], 0
	v_mfma_f32_16x16x32_bf16 v[4:7], v[4:7], v[124:127], 0
	v_mfma_f32_16x16x32_bf16 v[140:143], v[12:15], v[36:39], 0
	v_mfma_f32_16x16x32_bf16 v[148:151], v[12:15], v[52:55], 0
	v_mfma_f32_16x16x32_bf16 v[156:159], v[12:15], v[116:119], 0
	v_mfma_f32_16x16x32_bf16 v[160:163], v[8:11], v[128:131], v[4:7]
	v_mfma_f32_16x16x32_bf16 v[4:7], v[12:15], v[124:127], 0
	v_mfma_f32_16x16x32_bf16 v[136:139], v[8:11], v[44:47], v[134:137]
	v_mfma_f32_16x16x32_bf16 v[140:143], v[16:19], v[44:47], v[140:143]
	v_mfma_f32_16x16x32_bf16 v[144:147], v[8:11], v[60:63], v[144:147]
	v_mfma_f32_16x16x32_bf16 v[148:151], v[16:19], v[60:63], v[148:151]
	v_mfma_f32_16x16x32_bf16 v[152:155], v[8:11], v[120:123], v[152:155]
	v_mfma_f32_16x16x32_bf16 v[156:159], v[16:19], v[120:123], v[156:159]
	v_mfma_f32_16x16x32_bf16 v[164:167], v[16:19], v[128:131], v[4:7]
	s_setprio 0
	s_setprio 1
	v_mfma_f32_16x16x32_bf16 v[4:7], v[20:23], v[36:39], 0
	v_mfma_f32_16x16x32_bf16 v[168:171], v[24:27], v[44:47], v[4:7]
	v_mfma_f32_16x16x32_bf16 v[4:7], v[28:31], v[36:39], 0
	v_mfma_f32_16x16x32_bf16 v[172:175], v[32:35], v[44:47], v[4:7]
	v_mfma_f32_16x16x32_bf16 v[4:7], v[20:23], v[52:55], 0
	v_mfma_f32_16x16x32_bf16 v[176:179], v[24:27], v[60:63], v[4:7]
	v_mfma_f32_16x16x32_bf16 v[4:7], v[28:31], v[52:55], 0
	v_mfma_f32_16x16x32_bf16 v[180:183], v[32:35], v[60:63], v[4:7]
	v_mfma_f32_16x16x32_bf16 v[4:7], v[20:23], v[116:119], 0
	v_mfma_f32_16x16x32_bf16 v[184:187], v[24:27], v[120:123], v[4:7]
	v_mfma_f32_16x16x32_bf16 v[4:7], v[28:31], v[116:119], 0
	v_mfma_f32_16x16x32_bf16 v[120:123], v[32:35], v[120:123], v[4:7]
	v_mfma_f32_16x16x32_bf16 v[4:7], v[20:23], v[124:127], 0
	v_mfma_f32_16x16x32_bf16 v[188:191], v[24:27], v[128:131], v[4:7]
	v_mfma_f32_16x16x32_bf16 v[4:7], v[28:31], v[124:127], 0
	v_mfma_f32_16x16x32_bf16 v[128:131], v[32:35], v[128:131], v[4:7]
	s_setprio 0
	s_barrier
	s_add_i32 s16, 0, 0x18000
	s_add_i32 s76, 0, 0x1c000
	v_add_u32_e32 v134, s16, v243
	v_add_u32_e32 v135, s76, v243
	ds_read_b128 v[116:119], v134
	ds_read_b128 v[124:127], v134 offset:1024
	ds_read_b128 v[192:195], v134 offset:2048
	ds_read_b128 v[196:199], v134 offset:3072
	ds_read_b128 v[200:203], v135
	ds_read_b128 v[204:207], v135 offset:1024
	ds_read_b128 v[216:219], v135 offset:2048
	ds_read_b128 v[220:223], v135 offset:3072
	s_mov_b32 m0, s53
	s_mov_b64 s[8:9], s[42:43]
	ds_read_b128 v[44:47], v244 offset:32768
	ds_read_b128 v[52:55], v244 offset:33792
	ds_read_b128 v[60:63], v244 offset:34816
	ds_read_b128 v[224:227], v244 offset:35840
	ds_read_b128 v[228:231], v244 offset:36864
	ds_read_b128 v[232:235], v244 offset:37888
	ds_read_b128 v[248:251], v244 offset:38912
	ds_read_b128 v[208:211], v244 offset:39936
	s_nop 0
	global_load_lds_dwordx4 v238, s[8:9]
	s_mov_b32 m0, s57
	s_nop 0
	global_load_lds_dwordx4 v2, s[8:9]
	s_add_u32 s8, s42, s28
	s_addc_u32 s9, s43, s29
	s_mov_b32 m0, s58
	s_nop 0
	global_load_lds_dwordx4 v238, s[8:9]
	s_mov_b32 m0, s59
	s_nop 0
	global_load_lds_dwordx4 v2, s[8:9]
	s_waitcnt vmcnt(8)
	s_waitcnt lgkmcnt(0)
	s_barrier
	s_setprio 1
	s_waitcnt lgkmcnt(0)
	v_mfma_f32_16x16x32_bf16 v[4:7], v[116:119], v[44:47], v[68:71]
	v_mfma_f32_16x16x32_bf16 v[4:7], v[124:127], v[52:55], v[4:7]
	v_mfma_f32_16x16x32_bf16 v[8:11], v[192:195], v[44:47], v[72:75]
	v_mfma_f32_16x16x32_bf16 v[8:11], v[196:199], v[52:55], v[8:11]
	v_mfma_f32_16x16x32_bf16 v[12:15], v[116:119], v[60:63], v[76:79]
	v_mfma_f32_16x16x32_bf16 v[12:15], v[124:127], v[224:227], v[12:15]
	v_mfma_f32_16x16x32_bf16 v[16:19], v[192:195], v[60:63], v[80:83]
	v_mfma_f32_16x16x32_bf16 v[16:19], v[196:199], v[224:227], v[16:19]
	v_mfma_f32_16x16x32_bf16 v[20:23], v[116:119], v[228:231], v[84:87]
	v_mfma_f32_16x16x32_bf16 v[20:23], v[124:127], v[232:235], v[20:23]
	v_mfma_f32_16x16x32_bf16 v[24:27], v[192:195], v[228:231], v[88:91]
	v_mfma_f32_16x16x32_bf16 v[24:27], v[196:199], v[232:235], v[24:27]
	v_mfma_f32_16x16x32_bf16 v[28:31], v[116:119], v[248:251], v[92:95]
	v_mfma_f32_16x16x32_bf16 v[28:31], v[124:127], v[208:211], v[28:31]
	v_mfma_f32_16x16x32_bf16 v[32:35], v[192:195], v[248:251], v[96:99]
	v_mfma_f32_16x16x32_bf16 v[32:35], v[196:199], v[208:211], v[32:35]
	s_setprio 0
	s_setprio 1
	v_mfma_f32_16x16x32_bf16 v[36:39], v[200:203], v[44:47], v[100:103]
	v_mfma_f32_16x16x32_bf16 v[40:43], v[216:219], v[44:47], v[40:43]
	v_mfma_f32_16x16x32_bf16 v[36:39], v[204:207], v[52:55], v[36:39]
	v_mfma_f32_16x16x32_bf16 v[40:43], v[220:223], v[52:55], v[40:43]
	v_mfma_f32_16x16x32_bf16 v[44:47], v[200:203], v[60:63], v[104:107]
	v_mfma_f32_16x16x32_bf16 v[48:51], v[216:219], v[60:63], v[48:51]
	v_mfma_f32_16x16x32_bf16 v[52:55], v[200:203], v[228:231], v[108:111]
	v_mfma_f32_16x16x32_bf16 v[56:59], v[216:219], v[228:231], v[56:59]
	v_mfma_f32_16x16x32_bf16 v[60:63], v[200:203], v[248:251], v[112:115]
	v_mfma_f32_16x16x32_bf16 v[64:67], v[216:219], v[248:251], v[64:67]
	v_mfma_f32_16x16x32_bf16 v[44:47], v[204:207], v[224:227], v[44:47]
	v_mfma_f32_16x16x32_bf16 v[48:51], v[220:223], v[224:227], v[48:51]
	v_mfma_f32_16x16x32_bf16 v[52:55], v[204:207], v[232:235], v[52:55]
	v_mfma_f32_16x16x32_bf16 v[56:59], v[220:223], v[232:235], v[56:59]
	v_mfma_f32_16x16x32_bf16 v[60:63], v[204:207], v[208:211], v[60:63]
	v_mfma_f32_16x16x32_bf16 v[64:67], v[220:223], v[208:211], v[64:67]
	s_setprio 0
	s_barrier
	s_add_i32 s42, s16, s52
	s_mov_b64 s[8:9], s[18:19]
	s_mov_b32 m0, s42
	s_add_i32 s43, s42, 0x2000
	ds_read_b128 v[104:107], v244 offset:49152
	ds_read_b128 v[108:111], v244 offset:50176
	ds_read_b128 v[112:115], v244 offset:51200
	ds_read_b128 v[208:211], v244 offset:52224
	ds_read_b128 v[224:227], v244 offset:53248
	ds_read_b128 v[228:231], v244 offset:54272
	ds_read_b128 v[232:235], v244 offset:55296
	ds_read_b128 v[248:251], v244 offset:56320
	s_nop 0
	global_load_lds_dwordx4 v246, s[8:9]
	s_mov_b32 m0, s43
	s_nop 0
	global_load_lds_dwordx4 v245, s[8:9]
	s_add_u32 s8, s18, s28
	s_addc_u32 s9, s19, s29
	s_add_i32 s76, s76, s52
	s_mov_b32 m0, s76
	s_add_i32 s77, s76, 0x2000
	s_nop 0
	global_load_lds_dwordx4 v246, s[8:9]
	s_mov_b32 m0, s77
	s_nop 0
	global_load_lds_dwordx4 v245, s[8:9]
	s_waitcnt vmcnt(6)
	s_waitcnt lgkmcnt(0)
	s_barrier
	s_setprio 1
	s_waitcnt lgkmcnt(0)
	v_mfma_f32_16x16x32_bf16 v[68:71], v[116:119], v[104:107], v[136:139]
	v_mfma_f32_16x16x32_bf16 v[68:71], v[124:127], v[108:111], v[68:71]
	v_mfma_f32_16x16x32_bf16 v[72:75], v[192:195], v[104:107], v[140:143]
	v_mfma_f32_16x16x32_bf16 v[72:75], v[196:199], v[108:111], v[72:75]
	v_mfma_f32_16x16x32_bf16 v[76:79], v[116:119], v[112:115], v[144:147]
	v_mfma_f32_16x16x32_bf16 v[76:79], v[124:127], v[208:211], v[76:79]
	v_mfma_f32_16x16x32_bf16 v[80:83], v[192:195], v[112:115], v[148:151]
	v_mfma_f32_16x16x32_bf16 v[80:83], v[196:199], v[208:211], v[80:83]
	v_mfma_f32_16x16x32_bf16 v[84:87], v[116:119], v[224:227], v[152:155]
	v_mfma_f32_16x16x32_bf16 v[84:87], v[124:127], v[228:231], v[84:87]
	v_mfma_f32_16x16x32_bf16 v[88:91], v[192:195], v[224:227], v[156:159]
	v_mfma_f32_16x16x32_bf16 v[88:91], v[196:199], v[228:231], v[88:91]
	v_mfma_f32_16x16x32_bf16 v[92:95], v[116:119], v[232:235], v[160:163]
	v_mfma_f32_16x16x32_bf16 v[92:95], v[124:127], v[248:251], v[92:95]
	v_mfma_f32_16x16x32_bf16 v[96:99], v[192:195], v[232:235], v[164:167]
	v_mfma_f32_16x16x32_bf16 v[96:99], v[196:199], v[248:251], v[96:99]
	s_setprio 0
	s_setprio 1
	v_mfma_f32_16x16x32_bf16 v[100:103], v[200:203], v[104:107], v[168:171]
	v_mfma_f32_16x16x32_bf16 v[104:107], v[216:219], v[104:107], v[172:175]
	v_mfma_f32_16x16x32_bf16 v[100:103], v[204:207], v[108:111], v[100:103]
	v_mfma_f32_16x16x32_bf16 v[104:107], v[220:223], v[108:111], v[104:107]
	v_mfma_f32_16x16x32_bf16 v[108:111], v[200:203], v[112:115], v[176:179]
	v_mfma_f32_16x16x32_bf16 v[112:115], v[216:219], v[112:115], v[180:183]
	v_mfma_f32_16x16x32_bf16 v[116:119], v[200:203], v[224:227], v[184:187]
	v_mfma_f32_16x16x32_bf16 v[120:123], v[216:219], v[224:227], v[120:123]
	v_mfma_f32_16x16x32_bf16 v[124:127], v[200:203], v[232:235], v[188:191]
	v_mfma_f32_16x16x32_bf16 v[128:131], v[216:219], v[232:235], v[128:131]
	v_mfma_f32_16x16x32_bf16 v[108:111], v[204:207], v[208:211], v[108:111]
	v_mfma_f32_16x16x32_bf16 v[112:115], v[220:223], v[208:211], v[112:115]
	v_mfma_f32_16x16x32_bf16 v[116:119], v[204:207], v[228:231], v[116:119]
	v_mfma_f32_16x16x32_bf16 v[120:123], v[220:223], v[228:231], v[120:123]
	v_mfma_f32_16x16x32_bf16 v[124:127], v[204:207], v[248:251], v[124:127]
	v_mfma_f32_16x16x32_bf16 v[128:131], v[220:223], v[248:251], v[128:131]
	s_setprio 0
	s_barrier
	s_andn2_b64 vcc, exec, s[48:49]
	s_cbranch_vccnz .LBB0_1177
	s_add_u32 s78, s26, 0x200
	s_addc_u32 s79, s27, 0
	s_add_u32 s50, s50, 0x200
	s_addc_u32 s51, s51, 0
	s_mov_b32 s80, 4
	.p2align	6
	s_nop 0
	s_nop 0
	s_nop 0
	s_nop 0
	s_nop 0
	s_nop 0
	s_nop 0
	s_nop 0
	s_nop 0
	s_nop 0
	s_nop 0
	s_nop 0
